# diff-attn pass rewritten with 16x16x32 MFMA; row sums via ones-operand MFMA; cross-tile pipelined
# speedup vs baseline: 1.0728x; 1.0108x over previous
.La16_begin:
	s_lshr_b32 s72, s10, 3
	s_lshl_b32 s72, s72, 8
	s_lshl_b32 s0, s7, 2
	v_mov_b32_e32 v228, s0
	global_load_dword v230, v228, s[52:53]
	global_load_dword v231, v228, s[52:53] offset:1024
	s_lshl_b32 s0, s85, 1
	s_add_i32 s0, s0, s6
	s_lshl_b32 s0, s0, 3
	v_mov_b32_e32 v229, s0
	global_load_dwordx2 v[232:233], v229, s[28:29] offset:256
	s_lshl_b32 s0, s85, 2
	v_mov_b32_e32 v229, s0
	global_load_dword v234, v229, s[28:29] offset:512
	s_lshl_b32 s1, s33, 5
	s_add_i32 s0, s72, s1
	s_lshl_b32 s1, s0, 11
	s_lshl_b32 s73, s85, 8
	s_add_u32 s1, s1, s73
	s_lshl_b32 s73, s6, 7
	s_add_u32 s1, s1, s73
	s_add_u32 s96, s28, 304087040
	s_addc_u32 s97, s29, 0
	s_add_u32 s96, s96, s1
	s_addc_u32 s97, s97, 0
	s_lshl_b32 s1, s85, 8
	s_lshl_b32 s73, s6, 7
	s_add_u32 s1, s1, s73
	s_add_u32 s16, s28, 337641472
	s_addc_u32 s17, s29, 0
	s_add_u32 s16, s16, s1
	s_addc_u32 s17, s17, 0
	s_and_b32 s17, s17, 0xffff
	s_sub_u32 s18, 0x2000000, s1
	s_mov_b32 s19, 0x20000
	s_lshl_b32 s1, s85, 8
	s_add_u32 s60, s28, 371195904
	s_addc_u32 s61, s29, 0
	s_add_u32 s60, s60, s1
	s_addc_u32 s61, s61, 0
	s_and_b32 s61, s61, 0xffff
	s_sub_u32 s62, 0x2000000, s1
	s_mov_b32 s63, 0x20000
	s_lshl_b32 s1, s2, 18
	s_lshl_b32 s73, s6, 17
	s_add_u32 s1, s1, s73
	s_lshl_b32 s73, s33, 14
	s_add_u32 s1, s1, s73
	s_add_u32 s98, s26, s1
	s_addc_u32 s99, s27, 0
	s_lshl_b32 s0, s33, 10
	s_add_i32 s88, s0, 0
	s_add_i32 s90, s0, 16384
	s_add_i32 s91, s0, 24576
	s_add_i32 s89, s0, 8192
	s_add_i32 s92, s0, 32768
	s_add_i32 s93, s0, 40960
	s_add_i32 s0, s72, 0xffffff41
	s_ashr_i32 s0, s0, 6
	s_add_i32 s0, s0, 1
	s_and_b32 s12, s0, -2
	s_max_i32 s12, s12, 0
	s_add_i32 s0, s72, 446
	s_lshr_b32 s0, s0, 6
	s_add_i32 s0, s0, 1
	s_and_b32 s0, s0, -2
	s_min_u32 s84, s0, 256
	s_sub_u32 s13, s84, s12
	s_lshl_b32 s1, s33, 5
	s_add_i32 s1, s1, s72
	s_sub_u32 s87, 128, s1
	v_lshrrev_b32_e32 v236, 4, v204
	v_and_b32_e32 v237, 15, v204
	v_bfe_u32 v238, v204, 1, 3
	v_xor_b32_e32 v239, v236, v238
	v_lshlrev_b32_e32 v184, 7, v237
	v_lshl_add_u32 v184, v239, 4, v184
	v_xor_b32_e32 v185, 64, v184
	v_bfe_u32 v240, v204, 2, 2
	v_and_b32_e32 v241, 1, v204
	v_bfe_u32 v242, v204, 1, 1
	v_and_b32_e32 v243, 1, v236
	v_lshlrev_b32_e32 v244, 11, v236
	v_lshl_add_u32 v244, v240, 6, v244
	v_lshl_add_u32 v244, v241, 3, v244
	v_xor_b32_e32 v245, 0, v243
	v_xor_b32_e32 v246, 0, v242
	v_lshl_add_u32 v186, v245, 5, v244
	v_lshl_add_u32 v186, v246, 4, v186
	v_xor_b32_e32 v245, 0, v243
	v_xor_b32_e32 v246, 1, v242
	v_lshl_add_u32 v187, v245, 5, v244
	v_lshl_add_u32 v187, v246, 4, v187
	v_xor_b32_e32 v245, 1, v243
	v_xor_b32_e32 v246, 0, v242
	v_lshl_add_u32 v188, v245, 5, v244
	v_lshl_add_u32 v188, v246, 4, v188
	v_xor_b32_e32 v245, 1, v243
	v_xor_b32_e32 v246, 1, v242
	v_lshl_add_u32 v189, v245, 5, v244
	v_lshl_add_u32 v189, v246, 4, v189
	v_lshlrev_b32_e32 v201, 3, v236
	v_sub_u32_e32 v201, v201, v237
	s_lshl_b32 s0, s33, 6
	v_add_u32_e32 v245, s0, v204
	v_lshrrev_b32_e32 v246, 3, v245
	v_and_b32_e32 v247, 7, v245
	v_bfe_u32 v248, v246, 1, 3
	v_xor_b32_e32 v247, v247, v248
	v_lshrrev_b32_e32 v249, 5, v246
	v_lshlrev_b32_e32 v249, 5, v249
	v_bfe_u32 v250, v246, 2, 2
	v_lshl_add_u32 v249, v250, 3, v249
	v_bfe_u32 v250, v246, 4, 1
	v_lshl_add_u32 v249, v250, 2, v249
	v_and_b32_e32 v250, 3, v246
	v_add_u32_e32 v249, v249, v250
	v_lshlrev_b32_e32 v190, 11, v249
	v_lshl_add_u32 v190, v247, 4, v190
	s_add_i32 s0, s33, 0
	s_lshl_b32 s0, s0, 10
	v_lshl_add_u32 v245, v204, 4, s0
	v_lshrrev_b32_e32 v246, 11, v245
	v_bfe_u32 v247, v245, 6, 3
	v_lshl_add_u32 v246, v246, 3, v247
	v_bfe_u32 v247, v245, 4, 2
	v_bfe_u32 v248, v246, 2, 2
	v_xor_b32_e32 v247, v247, v248
	v_bfe_u32 v248, v245, 9, 2
	v_lshl_add_u32 v247, v248, 2, v247
	v_lshlrev_b32_e32 v191, 11, v246
	v_lshl_add_u32 v191, v247, 4, v191
	s_add_i32 s0, s33, 8
	s_lshl_b32 s0, s0, 10
	v_lshl_add_u32 v245, v204, 4, s0
	v_lshrrev_b32_e32 v246, 11, v245
	v_bfe_u32 v247, v245, 6, 3
	v_lshl_add_u32 v246, v246, 3, v247
	v_bfe_u32 v247, v245, 4, 2
	v_bfe_u32 v248, v246, 2, 2
	v_xor_b32_e32 v247, v247, v248
	v_bfe_u32 v248, v245, 9, 2
	v_lshl_add_u32 v247, v248, 2, v247
	v_lshlrev_b32_e32 v192, 11, v246
	v_lshl_add_u32 v192, v247, 4, v192
	v_lshlrev_b32_e32 v193, 11, v237
	v_lshl_add_u32 v193, v236, 4, v193
	v_add_u32_e32 v194, 0x8000, v193
	s_lshl_b32 s0, s33, 9
	s_add_i32 s0, s0, 49152
	v_lshl_add_u32 v197, v204, 2, s0
	v_lshl_add_u32 v198, v237, 2, s0
	v_lshl_add_u32 v199, v236, 4, s0
	v_lshlrev_b32_e32 v200, 11, v236
	v_lshl_add_u32 v200, v237, 2, v200
	s_mov_b32 s94, 0
	s_mov_b32 m0, s88
	s_nop 0
	buffer_load_dwordx4 v190, s[16:19], s94 offen lds
	s_mov_b32 m0, s90
	s_nop 0
	buffer_load_dwordx4 v191, s[60:63], s94 offen lds
	s_mov_b32 m0, s91
	s_nop 0
	buffer_load_dwordx4 v192, s[60:63], s94 offen lds
	s_mov_b32 s94, 0x20000
	s_mov_b32 m0, s89
	s_nop 0
	buffer_load_dwordx4 v190, s[16:19], s94 offen lds
	s_mov_b32 s94, 0x40000
	global_load_dwordx4 v[112:115], v193, s[96:97] offset:0
	global_load_dwordx4 v[116:119], v193, s[96:97] offset:64
	global_load_dwordx4 v[120:123], v194, s[96:97] offset:0
	global_load_dwordx4 v[124:127], v194, s[96:97] offset:64
	v_mov_b32_e32 v0, 0
	v_mov_b32_e32 v1, 0
	v_mov_b32_e32 v2, 0
	v_mov_b32_e32 v3, 0
	v_mov_b32_e32 v4, 0
	v_mov_b32_e32 v5, 0
	v_mov_b32_e32 v6, 0
	v_mov_b32_e32 v7, 0
	v_mov_b32_e32 v8, 0
	v_mov_b32_e32 v9, 0
	v_mov_b32_e32 v10, 0
	v_mov_b32_e32 v11, 0
	v_mov_b32_e32 v12, 0
	v_mov_b32_e32 v13, 0
	v_mov_b32_e32 v14, 0
	v_mov_b32_e32 v15, 0
	v_mov_b32_e32 v16, 0
	v_mov_b32_e32 v17, 0
	v_mov_b32_e32 v18, 0
	v_mov_b32_e32 v19, 0
	v_mov_b32_e32 v20, 0
	v_mov_b32_e32 v21, 0
	v_mov_b32_e32 v22, 0
	v_mov_b32_e32 v23, 0
	v_mov_b32_e32 v24, 0
	v_mov_b32_e32 v25, 0
	v_mov_b32_e32 v26, 0
	v_mov_b32_e32 v27, 0
	v_mov_b32_e32 v28, 0
	v_mov_b32_e32 v29, 0
	v_mov_b32_e32 v30, 0
	v_mov_b32_e32 v31, 0
	v_mov_b32_e32 v32, 0
	v_mov_b32_e32 v33, 0
	v_mov_b32_e32 v34, 0
	v_mov_b32_e32 v35, 0
	v_mov_b32_e32 v36, 0
	v_mov_b32_e32 v37, 0
	v_mov_b32_e32 v38, 0
	v_mov_b32_e32 v39, 0
	v_mov_b32_e32 v40, 0
	v_mov_b32_e32 v41, 0
	v_mov_b32_e32 v42, 0
	v_mov_b32_e32 v43, 0
	v_mov_b32_e32 v44, 0
	v_mov_b32_e32 v45, 0
	v_mov_b32_e32 v46, 0
	v_mov_b32_e32 v47, 0
	v_mov_b32_e32 v48, 0
	v_mov_b32_e32 v49, 0
	v_mov_b32_e32 v50, 0
	v_mov_b32_e32 v51, 0
	v_mov_b32_e32 v52, 0
	v_mov_b32_e32 v53, 0
	v_mov_b32_e32 v54, 0
	v_mov_b32_e32 v55, 0
	v_mov_b32_e32 v56, 0
	v_mov_b32_e32 v57, 0
	v_mov_b32_e32 v58, 0
	v_mov_b32_e32 v59, 0
	v_mov_b32_e32 v60, 0
	v_mov_b32_e32 v61, 0
	v_mov_b32_e32 v62, 0
	v_mov_b32_e32 v63, 0
	v_mov_b32_e32 v182, 0
	v_mov_b32_e32 v183, 0
	v_mov_b32_e32 v166, 0
	v_mov_b32_e32 v167, 0
	v_mov_b32_e32 v168, 0
	v_mov_b32_e32 v169, 0
	v_mov_b32_e32 v170, 0
	v_mov_b32_e32 v171, 0
	v_mov_b32_e32 v172, 0
	v_mov_b32_e32 v173, 0
	v_mov_b32_e32 v174, 0
	v_mov_b32_e32 v175, 0
	v_mov_b32_e32 v176, 0
	v_mov_b32_e32 v177, 0
	v_mov_b32_e32 v178, 0
	v_mov_b32_e32 v179, 0
	v_mov_b32_e32 v180, 0
	v_mov_b32_e32 v181, 0
	v_mov_b32_e32 v212, 0
	v_mov_b32_e32 v213, 0
	v_mov_b32_e32 v214, 0
	v_mov_b32_e32 v215, 0
	v_mov_b32_e32 v216, 0
	v_mov_b32_e32 v217, 0
	v_mov_b32_e32 v218, 0
	v_mov_b32_e32 v219, 0
	v_mov_b32_e32 v220, 0
	v_mov_b32_e32 v221, 0
	v_mov_b32_e32 v222, 0
	v_mov_b32_e32 v223, 0
	v_mov_b32_e32 v224, 0
	v_mov_b32_e32 v225, 0
	v_mov_b32_e32 v226, 0
	v_mov_b32_e32 v227, 0
	s_waitcnt vmcnt(0)
	s_nop 0
	v_readfirstlane_b32 s8, v230
	v_readfirstlane_b32 s9, v231
	v_readfirstlane_b32 s7, v234
	v_add_f32_e32 v232, v232, v233
	v_sqrt_f32_e32 v232, v232
	s_nop 0
	v_readfirstlane_b32 s11, v232
	v_mov_b32_e32 v234, 0
	v_lshlrev_b32_e32 v228, 16, v112
	v_and_b32_e32 v229, 0xffff0000, v112
	v_fmac_f32_e32 v234, v228, v228
	v_fmac_f32_e32 v234, v229, v229
	v_lshlrev_b32_e32 v228, 16, v113
	v_and_b32_e32 v229, 0xffff0000, v113
	v_fmac_f32_e32 v234, v228, v228
	v_fmac_f32_e32 v234, v229, v229
	v_lshlrev_b32_e32 v228, 16, v114
	v_and_b32_e32 v229, 0xffff0000, v114
	v_fmac_f32_e32 v234, v228, v228
	v_fmac_f32_e32 v234, v229, v229
	v_lshlrev_b32_e32 v228, 16, v115
	v_and_b32_e32 v229, 0xffff0000, v115
	v_fmac_f32_e32 v234, v228, v228
	v_fmac_f32_e32 v234, v229, v229
	v_lshlrev_b32_e32 v228, 16, v116
	v_and_b32_e32 v229, 0xffff0000, v116
	v_fmac_f32_e32 v234, v228, v228
	v_fmac_f32_e32 v234, v229, v229
	v_lshlrev_b32_e32 v228, 16, v117
	v_and_b32_e32 v229, 0xffff0000, v117
	v_fmac_f32_e32 v234, v228, v228
	v_fmac_f32_e32 v234, v229, v229
	v_lshlrev_b32_e32 v228, 16, v118
	v_and_b32_e32 v229, 0xffff0000, v118
	v_fmac_f32_e32 v234, v228, v228
	v_fmac_f32_e32 v234, v229, v229
	v_lshlrev_b32_e32 v228, 16, v119
	v_and_b32_e32 v229, 0xffff0000, v119
	v_fmac_f32_e32 v234, v228, v228
	v_fmac_f32_e32 v234, v229, v229
	ds_write_b32 v197, v234 offset:0
	v_mov_b32_e32 v235, 0
	v_lshlrev_b32_e32 v228, 16, v120
	v_and_b32_e32 v229, 0xffff0000, v120
	v_fmac_f32_e32 v235, v228, v228
	v_fmac_f32_e32 v235, v229, v229
	v_lshlrev_b32_e32 v228, 16, v121
	v_and_b32_e32 v229, 0xffff0000, v121
	v_fmac_f32_e32 v235, v228, v228
	v_fmac_f32_e32 v235, v229, v229
	v_lshlrev_b32_e32 v228, 16, v122
	v_and_b32_e32 v229, 0xffff0000, v122
	v_fmac_f32_e32 v235, v228, v228
	v_fmac_f32_e32 v235, v229, v229
	v_lshlrev_b32_e32 v228, 16, v123
	v_and_b32_e32 v229, 0xffff0000, v123
	v_fmac_f32_e32 v235, v228, v228
	v_fmac_f32_e32 v235, v229, v229
	v_lshlrev_b32_e32 v228, 16, v124
	v_and_b32_e32 v229, 0xffff0000, v124
	v_fmac_f32_e32 v235, v228, v228
	v_fmac_f32_e32 v235, v229, v229
	v_lshlrev_b32_e32 v228, 16, v125
	v_and_b32_e32 v229, 0xffff0000, v125
	v_fmac_f32_e32 v235, v228, v228
	v_fmac_f32_e32 v235, v229, v229
	v_lshlrev_b32_e32 v228, 16, v126
	v_and_b32_e32 v229, 0xffff0000, v126
	v_fmac_f32_e32 v235, v228, v228
	v_fmac_f32_e32 v235, v229, v229
	v_lshlrev_b32_e32 v228, 16, v127
	v_and_b32_e32 v229, 0xffff0000, v127
	v_fmac_f32_e32 v235, v228, v228
	v_fmac_f32_e32 v235, v229, v229
	ds_write_b32 v197, v235 offset:256
	s_waitcnt lgkmcnt(0)
	ds_read_b32 v236, v198 offset:0
	ds_read_b32 v237, v198 offset:64
	ds_read_b32 v238, v198 offset:128
	ds_read_b32 v239, v198 offset:192
	s_waitcnt lgkmcnt(2)
	v_add_f32_e32 v236, v236, v237
	s_waitcnt lgkmcnt(0)
	v_add_f32_e32 v238, v238, v239
	v_add_f32_e32 v236, v236, v238
	v_sqrt_f32_e32 v236, v236
	s_nop 0
	v_mov_b32_e32 v195, s7
	v_fmac_f32_e32 v195, s11, v236
	ds_read_b32 v236, v198 offset:256
	ds_read_b32 v237, v198 offset:320
	ds_read_b32 v238, v198 offset:384
	ds_read_b32 v239, v198 offset:448
	s_waitcnt lgkmcnt(2)
	v_add_f32_e32 v236, v236, v237
	s_waitcnt lgkmcnt(0)
	v_add_f32_e32 v238, v238, v239
	v_add_f32_e32 v236, v236, v238
	v_sqrt_f32_e32 v236, v236
	s_nop 0
	v_mov_b32_e32 v196, s7
	v_fmac_f32_e32 v196, s11, v236
	v_sub_f32_e32 v142, 0, v195
	v_mov_b32_e32 v143, v142
	v_mov_b32_e32 v144, v142
	v_mov_b32_e32 v145, v142
	v_sub_f32_e32 v146, 0, v196
	v_mov_b32_e32 v147, v146
	v_mov_b32_e32 v148, v146
	v_mov_b32_e32 v149, v146
	v_mov_b32_e32 v244, 0
	v_mov_b32_e32 v245, 0
	v_mov_b32_e32 v246, 0
	v_mov_b32_e32 v247, 0
	v_mov_b32_e32 v248, 0
	v_mov_b32_e32 v249, 0
	v_mov_b32_e32 v250, 0
	v_mov_b32_e32 v251, 0
	v_mov_b32_e32 v236, 0x3f803f80
	v_mov_b32_e32 v237, 0x3f803f80
	v_mov_b32_e32 v238, 0x3f803f80
	v_mov_b32_e32 v239, 0x3f803f80
	s_waitcnt vmcnt(0) lgkmcnt(0)
	s_barrier
	ds_read_b128 v[150:153], v184 offset:0
	ds_read_b128 v[154:157], v185 offset:0
	ds_read_b128 v[158:161], v184 offset:2048
	ds_read_b128 v[162:165], v185 offset:2048
	s_waitcnt lgkmcnt(3)
	v_mfma_f32_16x16x32_bf16 v[64:67], v[150:153], v[112:115], v[142:145]
	v_mfma_f32_16x16x32_bf16 v[68:71], v[150:153], v[120:123], v[146:149]
	ds_read_b128 v[150:153], v184 offset:4096
	s_waitcnt lgkmcnt(3)
	v_mfma_f32_16x16x32_bf16 v[64:67], v[154:157], v[116:119], v[64:67]
	v_mfma_f32_16x16x32_bf16 v[68:71], v[154:157], v[124:127], v[68:71]
	ds_read_b128 v[154:157], v185 offset:4096
	s_waitcnt lgkmcnt(3)
	v_mfma_f32_16x16x32_bf16 v[72:75], v[158:161], v[112:115], v[142:145]
	v_mfma_f32_16x16x32_bf16 v[76:79], v[158:161], v[120:123], v[146:149]
	ds_read_b128 v[158:161], v184 offset:6144
	s_waitcnt lgkmcnt(3)
	v_mfma_f32_16x16x32_bf16 v[72:75], v[162:165], v[116:119], v[72:75]
	v_mfma_f32_16x16x32_bf16 v[76:79], v[162:165], v[124:127], v[76:79]
	v_add3_u32 v232, v201, s87, 0
	v_med3_i32 v232, v232, 0, v210
	v_lshl_add_u32 v232, v232, 2, s75
	ds_read_b32 v228, v232 offset:0
	v_add3_u32 v233, v201, s87, 1
	v_med3_i32 v233, v233, 0, v210
	v_lshl_add_u32 v233, v233, 2, s75
	ds_read_b32 v229, v233 offset:0
	ds_read_b128 v[162:165], v185 offset:6144
	s_waitcnt lgkmcnt(5)
	v_mfma_f32_16x16x32_bf16 v[80:83], v[150:153], v[112:115], v[142:145]
	v_add3_u32 v234, v201, s87, 2
	v_med3_i32 v234, v234, 0, v210
	v_lshl_add_u32 v234, v234, 2, s75
	ds_read_b32 v230, v234 offset:0
	v_add3_u32 v235, v201, s87, 3
	v_med3_i32 v235, v235, 0, v210
	v_lshl_add_u32 v235, v235, 2, s75
	ds_read_b32 v231, v235 offset:0
	v_mfma_f32_16x16x32_bf16 v[84:87], v[150:153], v[120:123], v[146:149]
	s_waitcnt lgkmcnt(4)
	v_add_f32_e32 v64, v64, v228
	s_waitcnt lgkmcnt(3)
	v_add_f32_e32 v65, v65, v229
	v_mfma_f32_16x16x32_bf16 v[80:83], v[154:157], v[116:119], v[80:83]
	s_waitcnt lgkmcnt(1)
	v_add_f32_e32 v66, v66, v230
	s_waitcnt lgkmcnt(0)
	v_add_f32_e32 v67, v67, v231
	v_mfma_f32_16x16x32_bf16 v[84:87], v[154:157], v[124:127], v[84:87]
	v_add3_u32 v232, v201, s87, -16
	v_med3_i32 v232, v232, 0, v210
	v_lshl_add_u32 v232, v232, 2, s75
	ds_read_b32 v228, v232 offset:0
	v_add3_u32 v233, v201, s87, -15
	v_med3_i32 v233, v233, 0, v210
	v_lshl_add_u32 v233, v233, 2, s75
	ds_read_b32 v229, v233 offset:0
	v_mfma_f32_16x16x32_bf16 v[88:91], v[158:161], v[112:115], v[142:145]
	v_add3_u32 v234, v201, s87, -14
	v_med3_i32 v234, v234, 0, v210
	v_lshl_add_u32 v234, v234, 2, s75
	ds_read_b32 v230, v234 offset:0
	v_add3_u32 v235, v201, s87, -13
	v_med3_i32 v235, v235, 0, v210
	v_lshl_add_u32 v235, v235, 2, s75
	ds_read_b32 v231, v235 offset:0
	v_mfma_f32_16x16x32_bf16 v[92:95], v[158:161], v[120:123], v[146:149]
	s_waitcnt lgkmcnt(3)
	v_add_f32_e32 v68, v68, v228
	s_waitcnt lgkmcnt(2)
	v_add_f32_e32 v69, v69, v229
	v_mfma_f32_16x16x32_bf16 v[88:91], v[162:165], v[116:119], v[88:91]
	s_waitcnt lgkmcnt(1)
	v_add_f32_e32 v70, v70, v230
	s_waitcnt lgkmcnt(0)
	v_add_f32_e32 v71, v71, v231
	v_mfma_f32_16x16x32_bf16 v[92:95], v[162:165], v[124:127], v[92:95]
	v_exp_f32_e32 v64, v64
	v_exp_f32_e32 v65, v65
	v_exp_f32_e32 v66, v66
	v_exp_f32_e32 v67, v67
	v_exp_f32_e32 v68, v68
	v_exp_f32_e32 v69, v69
	v_exp_f32_e32 v70, v70
	v_exp_f32_e32 v71, v71
	v_add3_u32 v232, v201, s87, 4
	v_med3_i32 v232, v232, 0, v210
	v_lshl_add_u32 v232, v232, 2, s75
	ds_read_b32 v228, v232 offset:0
	v_add3_u32 v233, v201, s87, 5
	v_med3_i32 v233, v233, 0, v210
	v_lshl_add_u32 v233, v233, 2, s75
	ds_read_b32 v229, v233 offset:0
	v_add3_u32 v234, v201, s87, 6
	v_med3_i32 v234, v234, 0, v210
	v_lshl_add_u32 v234, v234, 2, s75
	ds_read_b32 v230, v234 offset:0
	v_add3_u32 v235, v201, s87, 7
	v_med3_i32 v235, v235, 0, v210
	v_lshl_add_u32 v235, v235, 2, s75
	ds_read_b32 v231, v235 offset:0
	s_waitcnt lgkmcnt(3)
	v_add_f32_e32 v72, v72, v228
	s_waitcnt lgkmcnt(2)
	v_add_f32_e32 v73, v73, v229
	s_waitcnt lgkmcnt(1)
	v_add_f32_e32 v74, v74, v230
	s_waitcnt lgkmcnt(0)
	v_add_f32_e32 v75, v75, v231
	v_add3_u32 v232, v201, s87, -12
	v_med3_i32 v232, v232, 0, v210
	v_lshl_add_u32 v232, v232, 2, s75
	ds_read_b32 v228, v232 offset:0
	v_add3_u32 v233, v201, s87, -11
	v_med3_i32 v233, v233, 0, v210
	v_lshl_add_u32 v233, v233, 2, s75
	ds_read_b32 v229, v233 offset:0
	v_add3_u32 v234, v201, s87, -10
	v_med3_i32 v234, v234, 0, v210
	v_lshl_add_u32 v234, v234, 2, s75
	ds_read_b32 v230, v234 offset:0
	v_add3_u32 v235, v201, s87, -9
	v_med3_i32 v235, v235, 0, v210
	v_lshl_add_u32 v235, v235, 2, s75
	ds_read_b32 v231, v235 offset:0
	s_waitcnt lgkmcnt(3)
	v_add_f32_e32 v76, v76, v228
	s_waitcnt lgkmcnt(2)
	v_add_f32_e32 v77, v77, v229
	s_waitcnt lgkmcnt(1)
	v_add_f32_e32 v78, v78, v230
	s_waitcnt lgkmcnt(0)
	v_add_f32_e32 v79, v79, v231
	v_exp_f32_e32 v72, v72
	v_exp_f32_e32 v73, v73
	v_exp_f32_e32 v74, v74
	v_exp_f32_e32 v75, v75
	v_exp_f32_e32 v76, v76
	v_exp_f32_e32 v77, v77
	v_exp_f32_e32 v78, v78
	v_exp_f32_e32 v79, v79
	v_cvt_pk_bf16_f32 v96, v64, v65
	v_cvt_pk_bf16_f32 v97, v66, v67
	v_cvt_pk_bf16_f32 v98, v72, v73
	v_cvt_pk_bf16_f32 v99, v74, v75
	v_cvt_pk_bf16_f32 v104, v68, v69
	v_cvt_pk_bf16_f32 v105, v70, v71
	v_cvt_pk_bf16_f32 v106, v76, v77
	v_cvt_pk_bf16_f32 v107, v78, v79
	v_add3_u32 v232, v201, s87, 32
	v_med3_i32 v232, v232, 0, v210
	v_lshl_add_u32 v232, v232, 2, s75
	ds_read_b32 v228, v232 offset:0
	v_add3_u32 v233, v201, s87, 33
	v_med3_i32 v233, v233, 0, v210
	v_lshl_add_u32 v233, v233, 2, s75
	ds_read_b32 v229, v233 offset:0
	v_add3_u32 v234, v201, s87, 34
	v_med3_i32 v234, v234, 0, v210
	v_lshl_add_u32 v234, v234, 2, s75
	ds_read_b32 v230, v234 offset:0
	v_add3_u32 v235, v201, s87, 35
	v_med3_i32 v235, v235, 0, v210
	v_lshl_add_u32 v235, v235, 2, s75
	ds_read_b32 v231, v235 offset:0
	s_waitcnt lgkmcnt(3)
	v_add_f32_e32 v80, v80, v228
	s_waitcnt lgkmcnt(2)
	v_add_f32_e32 v81, v81, v229
	s_waitcnt lgkmcnt(1)
	v_add_f32_e32 v82, v82, v230
	s_waitcnt lgkmcnt(0)
	v_add_f32_e32 v83, v83, v231
	v_add3_u32 v232, v201, s87, 16
	v_med3_i32 v232, v232, 0, v210
	v_lshl_add_u32 v232, v232, 2, s75
	ds_read_b32 v228, v232 offset:0
	v_add3_u32 v233, v201, s87, 17
	v_med3_i32 v233, v233, 0, v210
	v_lshl_add_u32 v233, v233, 2, s75
	ds_read_b32 v229, v233 offset:0
	v_add3_u32 v234, v201, s87, 18
	v_med3_i32 v234, v234, 0, v210
	v_lshl_add_u32 v234, v234, 2, s75
	ds_read_b32 v230, v234 offset:0
	v_add3_u32 v235, v201, s87, 19
	v_med3_i32 v235, v235, 0, v210
	v_lshl_add_u32 v235, v235, 2, s75
	ds_read_b32 v231, v235 offset:0
	s_waitcnt lgkmcnt(3)
	v_add_f32_e32 v84, v84, v228
	s_waitcnt lgkmcnt(2)
	v_add_f32_e32 v85, v85, v229
	s_waitcnt lgkmcnt(1)
	v_add_f32_e32 v86, v86, v230
	s_waitcnt lgkmcnt(0)
	v_add_f32_e32 v87, v87, v231
	v_exp_f32_e32 v80, v80
	v_exp_f32_e32 v81, v81
	v_exp_f32_e32 v82, v82
	v_exp_f32_e32 v83, v83
	v_exp_f32_e32 v84, v84
	v_exp_f32_e32 v85, v85
	v_exp_f32_e32 v86, v86
	v_exp_f32_e32 v87, v87
	v_add3_u32 v232, v201, s87, 36
	v_med3_i32 v232, v232, 0, v210
	v_lshl_add_u32 v232, v232, 2, s75
	ds_read_b32 v228, v232 offset:0
	v_add3_u32 v233, v201, s87, 37
	v_med3_i32 v233, v233, 0, v210
	v_lshl_add_u32 v233, v233, 2, s75
	ds_read_b32 v229, v233 offset:0
	v_add3_u32 v234, v201, s87, 38
	v_med3_i32 v234, v234, 0, v210
	v_lshl_add_u32 v234, v234, 2, s75
	ds_read_b32 v230, v234 offset:0
	v_add3_u32 v235, v201, s87, 39
	v_med3_i32 v235, v235, 0, v210
	v_lshl_add_u32 v235, v235, 2, s75
	ds_read_b32 v231, v235 offset:0
	s_waitcnt lgkmcnt(3)
	v_add_f32_e32 v88, v88, v228
	s_waitcnt lgkmcnt(2)
	v_add_f32_e32 v89, v89, v229
	s_waitcnt lgkmcnt(1)
	v_add_f32_e32 v90, v90, v230
	s_waitcnt lgkmcnt(0)
	v_add_f32_e32 v91, v91, v231
	v_add3_u32 v232, v201, s87, 20
	v_med3_i32 v232, v232, 0, v210
	v_lshl_add_u32 v232, v232, 2, s75
	ds_read_b32 v228, v232 offset:0
	v_add3_u32 v233, v201, s87, 21
	v_med3_i32 v233, v233, 0, v210
	v_lshl_add_u32 v233, v233, 2, s75
	ds_read_b32 v229, v233 offset:0
	v_add3_u32 v234, v201, s87, 22
	v_med3_i32 v234, v234, 0, v210
	v_lshl_add_u32 v234, v234, 2, s75
	ds_read_b32 v230, v234 offset:0
	v_add3_u32 v235, v201, s87, 23
	v_med3_i32 v235, v235, 0, v210
	v_lshl_add_u32 v235, v235, 2, s75
	ds_read_b32 v231, v235 offset:0
	s_waitcnt lgkmcnt(3)
	v_add_f32_e32 v92, v92, v228
	s_waitcnt lgkmcnt(2)
	v_add_f32_e32 v93, v93, v229
	s_waitcnt lgkmcnt(1)
	v_add_f32_e32 v94, v94, v230
	s_waitcnt lgkmcnt(0)
	v_add_f32_e32 v95, v95, v231
	v_exp_f32_e32 v88, v88
	v_exp_f32_e32 v89, v89
	v_exp_f32_e32 v90, v90
	v_exp_f32_e32 v91, v91
	v_exp_f32_e32 v92, v92
	v_exp_f32_e32 v93, v93
	v_exp_f32_e32 v94, v94
	v_exp_f32_e32 v95, v95
	v_cvt_pk_bf16_f32 v100, v80, v81
	v_cvt_pk_bf16_f32 v101, v82, v83
	v_cvt_pk_bf16_f32 v102, v88, v89
	v_cvt_pk_bf16_f32 v103, v90, v91
	v_cvt_pk_bf16_f32 v108, v84, v85
	v_cvt_pk_bf16_f32 v109, v86, v87
	v_cvt_pk_bf16_f32 v110, v92, v93
	v_cvt_pk_bf16_f32 v111, v94, v95
	s_waitcnt vmcnt(0) lgkmcnt(0)
	s_barrier
	s_cmp_eq_u32 s12, 0
	s_cbranch_scc1 .La_noleft
	v_sub_f32_e32 v142, s8, v195
	v_mov_b32_e32 v143, v142
	v_mov_b32_e32 v144, v142
	v_mov_b32_e32 v145, v142
	v_sub_f32_e32 v146, s8, v196
	v_mov_b32_e32 v147, v146
	v_mov_b32_e32 v148, v146
	v_mov_b32_e32 v149, v146
.La_noleft:
	s_mov_b32 s95, 0
.La_loop:
	s_add_i32 s0, s95, 1
	s_cmp_lg_u32 s0, s12
	s_cbranch_scc1 .La_c1_p0
	v_sub_f32_e32 v142, 0, v195
	v_mov_b32_e32 v143, v142
	v_mov_b32_e32 v144, v142
	v_mov_b32_e32 v145, v142
	v_sub_f32_e32 v146, 0, v196
	v_mov_b32_e32 v147, v146
	v_mov_b32_e32 v148, v146
	v_mov_b32_e32 v149, v146
.La_c1_p0:
	s_cmp_lg_u32 s0, s84
	s_cbranch_scc1 .La_c2_p0
	v_sub_f32_e32 v142, s9, v195
	v_mov_b32_e32 v143, v142
	v_mov_b32_e32 v144, v142
	v_mov_b32_e32 v145, v142
	v_sub_f32_e32 v146, s9, v196
	v_mov_b32_e32 v147, v146
	v_mov_b32_e32 v148, v146
	v_mov_b32_e32 v149, v146
.La_c2_p0:
	s_cmpk_lg_u32 s0, 256
	s_cbranch_scc1 .La_c3_p0
	v_mov_b32_e32 v142, 0xf149f2ca
	v_mov_b32_e32 v143, v142
	v_mov_b32_e32 v144, v142
	v_mov_b32_e32 v145, v142
	v_mov_b32_e32 v146, 0xf149f2ca
	v_mov_b32_e32 v147, v146
	v_mov_b32_e32 v148, v146
	v_mov_b32_e32 v149, v146
.La_c3_p0:
	s_add_i32 s87, s87, 64
	s_sub_u32 s0, s0, s12
	s_cmp_lt_u32 s0, s13
	s_cbranch_scc1 .La_band0
	ds_read_b128 v[150:153], v184 offset:8192
	ds_read_b128 v[154:157], v185 offset:8192
	ds_read_b128 v[158:161], v184 offset:10240
	s_add_i32 s1, s94, 0xfffe0000
	v_mfma_f32_16x16x32_bf16 v[16:19], v[216:219], v[166:169], v[16:19]
	s_mov_b32 m0, s88
	s_nop 0
	buffer_load_dwordx4 v190, s[16:19], s94 offen lds
	v_mfma_f32_16x16x32_bf16 v[48:51], v[224:227], v[166:169], v[48:51]
	s_mov_b32 m0, s92
	s_nop 0
	buffer_load_dwordx4 v191, s[60:63], s1 offen lds
	v_mfma_f32_16x16x32_bf16 v[20:23], v[216:219], v[170:173], v[20:23]
	s_mov_b32 m0, s93
	s_nop 0
	buffer_load_dwordx4 v192, s[60:63], s1 offen lds
	v_mfma_f32_16x16x32_bf16 v[52:55], v[224:227], v[170:173], v[52:55]
	v_mfma_f32_16x16x32_bf16 v[24:27], v[216:219], v[174:177], v[24:27]
	v_mfma_f32_16x16x32_bf16 v[56:59], v[224:227], v[174:177], v[56:59]
	v_mfma_f32_16x16x32_bf16 v[28:31], v[216:219], v[178:181], v[28:31]
	v_mfma_f32_16x16x32_bf16 v[60:63], v[224:227], v[178:181], v[60:63]
	s_add_i32 s94, s94, 0x20000
	ds_read_b128 v[162:165], v185 offset:10240
	s_waitcnt lgkmcnt(3)
	v_mfma_f32_16x16x32_bf16 v[64:67], v[150:153], v[112:115], v[142:145]
	v_mfma_f32_16x16x32_bf16 v[68:71], v[150:153], v[120:123], v[146:149]
	ds_read_b128 v[150:153], v184 offset:12288
	s_waitcnt lgkmcnt(3)
	v_mfma_f32_16x16x32_bf16 v[64:67], v[154:157], v[116:119], v[64:67]
	v_mfma_f32_16x16x32_bf16 v[68:71], v[154:157], v[124:127], v[68:71]
	ds_read_b128 v[154:157], v185 offset:12288
	s_waitcnt lgkmcnt(3)
	v_mfma_f32_16x16x32_bf16 v[72:75], v[158:161], v[112:115], v[142:145]
	v_mfma_f32_16x16x32_bf16 v[76:79], v[158:161], v[120:123], v[146:149]
	ds_read_b128 v[158:161], v184 offset:14336
	s_waitcnt lgkmcnt(3)
	v_mfma_f32_16x16x32_bf16 v[72:75], v[162:165], v[116:119], v[72:75]
	v_mfma_f32_16x16x32_bf16 v[76:79], v[162:165], v[124:127], v[76:79]
	v_exp_f32_e32 v64, v64
	v_exp_f32_e32 v65, v65
	ds_read_b128 v[162:165], v185 offset:14336
	s_waitcnt lgkmcnt(3)
	v_mfma_f32_16x16x32_bf16 v[80:83], v[150:153], v[112:115], v[142:145]
	v_exp_f32_e32 v66, v66
	v_exp_f32_e32 v67, v67
	v_mfma_f32_16x16x32_bf16 v[84:87], v[150:153], v[120:123], v[146:149]
	v_exp_f32_e32 v68, v68
	v_exp_f32_e32 v69, v69
	ds_read_b64_tr_b16 v[166:167], v186 offset:16384
	ds_read_b64_tr_b16 v[168:169], v187 offset:16640
	s_waitcnt lgkmcnt(4)
	v_mfma_f32_16x16x32_bf16 v[80:83], v[154:157], v[116:119], v[80:83]
	v_exp_f32_e32 v70, v70
	v_exp_f32_e32 v71, v71
	v_mfma_f32_16x16x32_bf16 v[84:87], v[154:157], v[124:127], v[84:87]
	v_exp_f32_e32 v72, v72
	v_exp_f32_e32 v73, v73
	ds_read_b64_tr_b16 v[170:171], v188 offset:16384
	ds_read_b64_tr_b16 v[172:173], v189 offset:16640
	s_waitcnt lgkmcnt(5)
	v_mfma_f32_16x16x32_bf16 v[88:91], v[158:161], v[112:115], v[142:145]
	v_exp_f32_e32 v74, v74
	v_exp_f32_e32 v75, v75
	v_mfma_f32_16x16x32_bf16 v[92:95], v[158:161], v[120:123], v[146:149]
	v_exp_f32_e32 v76, v76
	v_exp_f32_e32 v77, v77
	ds_read_b64_tr_b16 v[174:175], v186 offset:16896
	ds_read_b64_tr_b16 v[176:177], v187 offset:17152
	s_waitcnt lgkmcnt(6)
	v_mfma_f32_16x16x32_bf16 v[88:91], v[162:165], v[116:119], v[88:91]
	v_exp_f32_e32 v78, v78
	v_exp_f32_e32 v79, v79
	v_mfma_f32_16x16x32_bf16 v[92:95], v[162:165], v[124:127], v[92:95]
	v_cvt_pk_bf16_f32 v212, v64, v65
	v_cvt_pk_bf16_f32 v213, v66, v67
	ds_read_b64_tr_b16 v[178:179], v188 offset:16896
	ds_read_b64_tr_b16 v[180:181], v189 offset:17152
	s_waitcnt lgkmcnt(6)
	v_mfma_f32_16x16x32_bf16 v[0:3], v[96:99], v[166:169], v[0:3]
	v_cvt_pk_bf16_f32 v214, v72, v73
	v_cvt_pk_bf16_f32 v215, v74, v75
	v_mfma_f32_16x16x32_bf16 v[32:35], v[104:107], v[166:169], v[32:35]
	v_cvt_pk_bf16_f32 v220, v68, v69
	v_cvt_pk_bf16_f32 v221, v70, v71
	v_mfma_f32_16x16x32_bf16 v[244:247], v[96:99], v[236:239], v[244:247]
	v_mfma_f32_16x16x32_bf16 v[248:251], v[104:107], v[236:239], v[248:251]
	ds_read_b64_tr_b16 v[166:167], v186 offset:17408
	ds_read_b64_tr_b16 v[168:169], v187 offset:17664
	s_waitcnt lgkmcnt(6)
	v_mfma_f32_16x16x32_bf16 v[4:7], v[96:99], v[170:173], v[4:7]
	v_cvt_pk_bf16_f32 v222, v76, v77
	v_cvt_pk_bf16_f32 v223, v78, v79
	v_mfma_f32_16x16x32_bf16 v[36:39], v[104:107], v[170:173], v[36:39]
	v_exp_f32_e32 v80, v80
	v_exp_f32_e32 v81, v81
	ds_read_b64_tr_b16 v[170:171], v188 offset:17408
	ds_read_b64_tr_b16 v[172:173], v189 offset:17664
	s_waitcnt lgkmcnt(6)
	v_mfma_f32_16x16x32_bf16 v[8:11], v[96:99], v[174:177], v[8:11]
	v_exp_f32_e32 v82, v82
	v_exp_f32_e32 v83, v83
	v_mfma_f32_16x16x32_bf16 v[40:43], v[104:107], v[174:177], v[40:43]
	v_exp_f32_e32 v84, v84
	v_exp_f32_e32 v85, v85
	ds_read_b64_tr_b16 v[174:175], v186 offset:17920
	ds_read_b64_tr_b16 v[176:177], v187 offset:18176
	s_waitcnt lgkmcnt(6)
	v_mfma_f32_16x16x32_bf16 v[12:15], v[96:99], v[178:181], v[12:15]
	v_exp_f32_e32 v86, v86
	v_exp_f32_e32 v87, v87
	v_mfma_f32_16x16x32_bf16 v[44:47], v[104:107], v[178:181], v[44:47]
	v_exp_f32_e32 v88, v88
	v_exp_f32_e32 v89, v89
	ds_read_b64_tr_b16 v[178:179], v188 offset:17920
	ds_read_b64_tr_b16 v[180:181], v189 offset:18176
	s_waitcnt lgkmcnt(6)
	v_mfma_f32_16x16x32_bf16 v[16:19], v[96:99], v[166:169], v[16:19]
	v_exp_f32_e32 v90, v90
	v_exp_f32_e32 v91, v91
	v_mfma_f32_16x16x32_bf16 v[48:51], v[104:107], v[166:169], v[48:51]
	v_exp_f32_e32 v92, v92
	v_exp_f32_e32 v93, v93
	ds_read_b64_tr_b16 v[166:167], v186 offset:24576
	ds_read_b64_tr_b16 v[168:169], v187 offset:24832
	s_waitcnt lgkmcnt(6)
	v_mfma_f32_16x16x32_bf16 v[20:23], v[96:99], v[170:173], v[20:23]
	v_exp_f32_e32 v94, v94
	v_exp_f32_e32 v95, v95
	v_mfma_f32_16x16x32_bf16 v[52:55], v[104:107], v[170:173], v[52:55]
	v_cvt_pk_bf16_f32 v216, v80, v81
	v_cvt_pk_bf16_f32 v217, v82, v83
	ds_read_b64_tr_b16 v[170:171], v188 offset:24576
	ds_read_b64_tr_b16 v[172:173], v189 offset:24832
	s_waitcnt lgkmcnt(6)
	v_mfma_f32_16x16x32_bf16 v[24:27], v[96:99], v[174:177], v[24:27]
	v_cvt_pk_bf16_f32 v218, v88, v89
	v_cvt_pk_bf16_f32 v219, v90, v91
	v_mfma_f32_16x16x32_bf16 v[56:59], v[104:107], v[174:177], v[56:59]
	v_cvt_pk_bf16_f32 v224, v84, v85
	v_cvt_pk_bf16_f32 v225, v86, v87
	ds_read_b64_tr_b16 v[174:175], v186 offset:25088
	ds_read_b64_tr_b16 v[176:177], v187 offset:25344
	s_waitcnt lgkmcnt(6)
	v_mfma_f32_16x16x32_bf16 v[28:31], v[96:99], v[178:181], v[28:31]
	v_cvt_pk_bf16_f32 v226, v92, v93
	v_cvt_pk_bf16_f32 v227, v94, v95
	v_mfma_f32_16x16x32_bf16 v[60:63], v[104:107], v[178:181], v[60:63]
	ds_read_b64_tr_b16 v[178:179], v188 offset:25088
	ds_read_b64_tr_b16 v[180:181], v189 offset:25344
	s_waitcnt lgkmcnt(6)
	v_mfma_f32_16x16x32_bf16 v[0:3], v[100:103], v[166:169], v[0:3]
	v_mfma_f32_16x16x32_bf16 v[32:35], v[108:111], v[166:169], v[32:35]
	v_mfma_f32_16x16x32_bf16 v[244:247], v[100:103], v[236:239], v[244:247]
	v_mfma_f32_16x16x32_bf16 v[248:251], v[108:111], v[236:239], v[248:251]
	ds_read_b64_tr_b16 v[166:167], v186 offset:25600
	ds_read_b64_tr_b16 v[168:169], v187 offset:25856
	s_waitcnt lgkmcnt(6)
	v_mfma_f32_16x16x32_bf16 v[4:7], v[100:103], v[170:173], v[4:7]
	v_mfma_f32_16x16x32_bf16 v[36:39], v[108:111], v[170:173], v[36:39]
	ds_read_b64_tr_b16 v[170:171], v188 offset:25600
	ds_read_b64_tr_b16 v[172:173], v189 offset:25856
	s_waitcnt lgkmcnt(6)
	v_mfma_f32_16x16x32_bf16 v[8:11], v[100:103], v[174:177], v[8:11]
	v_mfma_f32_16x16x32_bf16 v[40:43], v[108:111], v[174:177], v[40:43]
	ds_read_b64_tr_b16 v[174:175], v186 offset:26112
	ds_read_b64_tr_b16 v[176:177], v187 offset:26368
	s_waitcnt lgkmcnt(6)
	v_mfma_f32_16x16x32_bf16 v[12:15], v[100:103], v[178:181], v[12:15]
	v_mfma_f32_16x16x32_bf16 v[44:47], v[108:111], v[178:181], v[44:47]
	ds_read_b64_tr_b16 v[178:179], v188 offset:26112
	ds_read_b64_tr_b16 v[180:181], v189 offset:26368
	s_waitcnt vmcnt(0) lgkmcnt(0)
	s_barrier
	s_branch .La_done0
.La_band0:
	ds_read_b128 v[150:153], v184 offset:8192
	ds_read_b128 v[154:157], v185 offset:8192
	ds_read_b128 v[158:161], v184 offset:10240
	s_add_i32 s1, s94, 0xfffe0000
	v_mfma_f32_16x16x32_bf16 v[16:19], v[216:219], v[166:169], v[16:19]
	s_mov_b32 m0, s88
	s_nop 0
	buffer_load_dwordx4 v190, s[16:19], s94 offen lds
	v_mfma_f32_16x16x32_bf16 v[48:51], v[224:227], v[166:169], v[48:51]
	s_mov_b32 m0, s92
	s_nop 0
	buffer_load_dwordx4 v191, s[60:63], s1 offen lds
	v_mfma_f32_16x16x32_bf16 v[20:23], v[216:219], v[170:173], v[20:23]
	s_mov_b32 m0, s93
	s_nop 0
	buffer_load_dwordx4 v192, s[60:63], s1 offen lds
	v_mfma_f32_16x16x32_bf16 v[52:55], v[224:227], v[170:173], v[52:55]
	v_mfma_f32_16x16x32_bf16 v[24:27], v[216:219], v[174:177], v[24:27]
	v_mfma_f32_16x16x32_bf16 v[56:59], v[224:227], v[174:177], v[56:59]
	v_mfma_f32_16x16x32_bf16 v[28:31], v[216:219], v[178:181], v[28:31]
	v_mfma_f32_16x16x32_bf16 v[60:63], v[224:227], v[178:181], v[60:63]
	s_add_i32 s94, s94, 0x20000
	ds_read_b128 v[162:165], v185 offset:10240
	s_waitcnt lgkmcnt(3)
	v_mfma_f32_16x16x32_bf16 v[64:67], v[150:153], v[112:115], v[142:145]
	v_mfma_f32_16x16x32_bf16 v[68:71], v[150:153], v[120:123], v[146:149]
	ds_read_b128 v[150:153], v184 offset:12288
	s_waitcnt lgkmcnt(3)
	v_mfma_f32_16x16x32_bf16 v[64:67], v[154:157], v[116:119], v[64:67]
	v_mfma_f32_16x16x32_bf16 v[68:71], v[154:157], v[124:127], v[68:71]
	ds_read_b128 v[154:157], v185 offset:12288
	s_waitcnt lgkmcnt(3)
	v_mfma_f32_16x16x32_bf16 v[72:75], v[158:161], v[112:115], v[142:145]
	v_mfma_f32_16x16x32_bf16 v[76:79], v[158:161], v[120:123], v[146:149]
	ds_read_b128 v[158:161], v184 offset:14336
	s_waitcnt lgkmcnt(3)
	v_mfma_f32_16x16x32_bf16 v[72:75], v[162:165], v[116:119], v[72:75]
	v_mfma_f32_16x16x32_bf16 v[76:79], v[162:165], v[124:127], v[76:79]
	v_add3_u32 v232, v201, s87, 0
	v_med3_i32 v232, v232, 0, v210
	v_lshl_add_u32 v232, v232, 2, s75
	ds_read_b32 v228, v232 offset:0
	v_add3_u32 v233, v201, s87, 1
	v_med3_i32 v233, v233, 0, v210
	v_lshl_add_u32 v233, v233, 2, s75
	ds_read_b32 v229, v233 offset:0
	ds_read_b128 v[162:165], v185 offset:14336
	s_waitcnt lgkmcnt(5)
	v_mfma_f32_16x16x32_bf16 v[80:83], v[150:153], v[112:115], v[142:145]
	v_add3_u32 v234, v201, s87, 2
	v_med3_i32 v234, v234, 0, v210
	v_lshl_add_u32 v234, v234, 2, s75
	ds_read_b32 v230, v234 offset:0
	v_add3_u32 v235, v201, s87, 3
	v_med3_i32 v235, v235, 0, v210
	v_lshl_add_u32 v235, v235, 2, s75
	ds_read_b32 v231, v235 offset:0
	v_mfma_f32_16x16x32_bf16 v[84:87], v[150:153], v[120:123], v[146:149]
	s_waitcnt lgkmcnt(4)
	v_add_f32_e32 v64, v64, v228
	s_waitcnt lgkmcnt(3)
	v_add_f32_e32 v65, v65, v229
	ds_read_b64_tr_b16 v[166:167], v186 offset:16384
	ds_read_b64_tr_b16 v[168:169], v187 offset:16640
	v_mfma_f32_16x16x32_bf16 v[80:83], v[154:157], v[116:119], v[80:83]
	s_waitcnt lgkmcnt(3)
	v_add_f32_e32 v66, v66, v230
	s_waitcnt lgkmcnt(2)
	v_add_f32_e32 v67, v67, v231
	v_mfma_f32_16x16x32_bf16 v[84:87], v[154:157], v[124:127], v[84:87]
	v_add3_u32 v232, v201, s87, -16
	v_med3_i32 v232, v232, 0, v210
	v_lshl_add_u32 v232, v232, 2, s75
	ds_read_b32 v228, v232 offset:0
	v_add3_u32 v233, v201, s87, -15
	v_med3_i32 v233, v233, 0, v210
	v_lshl_add_u32 v233, v233, 2, s75
	ds_read_b32 v229, v233 offset:0
	ds_read_b64_tr_b16 v[170:171], v188 offset:16384
	ds_read_b64_tr_b16 v[172:173], v189 offset:16640
	v_mfma_f32_16x16x32_bf16 v[88:91], v[158:161], v[112:115], v[142:145]
	v_add3_u32 v234, v201, s87, -14
	v_med3_i32 v234, v234, 0, v210
	v_lshl_add_u32 v234, v234, 2, s75
	ds_read_b32 v230, v234 offset:0
	v_add3_u32 v235, v201, s87, -13
	v_med3_i32 v235, v235, 0, v210
	v_lshl_add_u32 v235, v235, 2, s75
	ds_read_b32 v231, v235 offset:0
	v_mfma_f32_16x16x32_bf16 v[92:95], v[158:161], v[120:123], v[146:149]
	s_waitcnt lgkmcnt(5)
	v_add_f32_e32 v68, v68, v228
	s_waitcnt lgkmcnt(4)
	v_add_f32_e32 v69, v69, v229
	ds_read_b64_tr_b16 v[174:175], v186 offset:16896
	ds_read_b64_tr_b16 v[176:177], v187 offset:17152
	v_mfma_f32_16x16x32_bf16 v[88:91], v[162:165], v[116:119], v[88:91]
	s_waitcnt lgkmcnt(3)
	v_add_f32_e32 v70, v70, v230
	s_waitcnt lgkmcnt(2)
	v_add_f32_e32 v71, v71, v231
	v_mfma_f32_16x16x32_bf16 v[92:95], v[162:165], v[124:127], v[92:95]
	v_exp_f32_e32 v64, v64
	v_exp_f32_e32 v65, v65
	ds_read_b64_tr_b16 v[178:179], v188 offset:16896
	ds_read_b64_tr_b16 v[180:181], v189 offset:17152
	v_mfma_f32_16x16x32_bf16 v[0:3], v[96:99], v[166:169], v[0:3]
	v_exp_f32_e32 v66, v66
	v_exp_f32_e32 v67, v67
	v_exp_f32_e32 v68, v68
	v_exp_f32_e32 v69, v69
	v_mfma_f32_16x16x32_bf16 v[32:35], v[104:107], v[166:169], v[32:35]
	v_exp_f32_e32 v70, v70
	v_exp_f32_e32 v71, v71
	v_add3_u32 v232, v201, s87, 4
	v_med3_i32 v232, v232, 0, v210
	v_lshl_add_u32 v232, v232, 2, s75
	ds_read_b32 v228, v232 offset:0
	v_add3_u32 v233, v201, s87, 5
	v_med3_i32 v233, v233, 0, v210
	v_lshl_add_u32 v233, v233, 2, s75
	ds_read_b32 v229, v233 offset:0
	v_mfma_f32_16x16x32_bf16 v[244:247], v[96:99], v[236:239], v[244:247]
	v_mfma_f32_16x16x32_bf16 v[248:251], v[104:107], v[236:239], v[248:251]
	ds_read_b64_tr_b16 v[166:167], v186 offset:17408
	ds_read_b64_tr_b16 v[168:169], v187 offset:17664
	v_mfma_f32_16x16x32_bf16 v[4:7], v[96:99], v[170:173], v[4:7]
	v_add3_u32 v234, v201, s87, 6
	v_med3_i32 v234, v234, 0, v210
	v_lshl_add_u32 v234, v234, 2, s75
	ds_read_b32 v230, v234 offset:0
	v_add3_u32 v235, v201, s87, 7
	v_med3_i32 v235, v235, 0, v210
	v_lshl_add_u32 v235, v235, 2, s75
	ds_read_b32 v231, v235 offset:0
	s_waitcnt lgkmcnt(5)
	v_add_f32_e32 v72, v72, v228
	s_waitcnt lgkmcnt(4)
	v_add_f32_e32 v73, v73, v229
	v_mfma_f32_16x16x32_bf16 v[36:39], v[104:107], v[170:173], v[36:39]
	s_waitcnt lgkmcnt(1)
	v_add_f32_e32 v74, v74, v230
	s_waitcnt lgkmcnt(0)
	v_add_f32_e32 v75, v75, v231
	v_add3_u32 v232, v201, s87, -12
	v_med3_i32 v232, v232, 0, v210
	v_lshl_add_u32 v232, v232, 2, s75
	ds_read_b32 v228, v232 offset:0
	v_add3_u32 v233, v201, s87, -11
	v_med3_i32 v233, v233, 0, v210
	v_lshl_add_u32 v233, v233, 2, s75
	ds_read_b32 v229, v233 offset:0
	ds_read_b64_tr_b16 v[170:171], v188 offset:17408
	ds_read_b64_tr_b16 v[172:173], v189 offset:17664
	v_mfma_f32_16x16x32_bf16 v[8:11], v[96:99], v[174:177], v[8:11]
	v_add3_u32 v234, v201, s87, -10
	v_med3_i32 v234, v234, 0, v210
	v_lshl_add_u32 v234, v234, 2, s75
	ds_read_b32 v230, v234 offset:0
	v_add3_u32 v235, v201, s87, -9
	v_med3_i32 v235, v235, 0, v210
	v_lshl_add_u32 v235, v235, 2, s75
	ds_read_b32 v231, v235 offset:0
	s_waitcnt lgkmcnt(5)
	v_add_f32_e32 v76, v76, v228
	s_waitcnt lgkmcnt(4)
	v_add_f32_e32 v77, v77, v229
	v_mfma_f32_16x16x32_bf16 v[40:43], v[104:107], v[174:177], v[40:43]
	s_waitcnt lgkmcnt(1)
	v_add_f32_e32 v78, v78, v230
	s_waitcnt lgkmcnt(0)
	v_add_f32_e32 v79, v79, v231
	v_exp_f32_e32 v72, v72
	v_exp_f32_e32 v73, v73
	ds_read_b64_tr_b16 v[174:175], v186 offset:17920
	ds_read_b64_tr_b16 v[176:177], v187 offset:18176
	v_mfma_f32_16x16x32_bf16 v[12:15], v[96:99], v[178:181], v[12:15]
	v_exp_f32_e32 v74, v74
	v_exp_f32_e32 v75, v75
	v_exp_f32_e32 v76, v76
	v_exp_f32_e32 v77, v77
	v_mfma_f32_16x16x32_bf16 v[44:47], v[104:107], v[178:181], v[44:47]
	v_exp_f32_e32 v78, v78
	v_exp_f32_e32 v79, v79
	v_cvt_pk_bf16_f32 v212, v64, v65
	v_cvt_pk_bf16_f32 v213, v66, v67
	ds_read_b64_tr_b16 v[178:179], v188 offset:17920
	ds_read_b64_tr_b16 v[180:181], v189 offset:18176
	v_mfma_f32_16x16x32_bf16 v[16:19], v[96:99], v[166:169], v[16:19]
	v_cvt_pk_bf16_f32 v214, v72, v73
	v_cvt_pk_bf16_f32 v215, v74, v75
	v_cvt_pk_bf16_f32 v220, v68, v69
	v_cvt_pk_bf16_f32 v221, v70, v71
	v_mfma_f32_16x16x32_bf16 v[48:51], v[104:107], v[166:169], v[48:51]
	v_cvt_pk_bf16_f32 v222, v76, v77
	v_cvt_pk_bf16_f32 v223, v78, v79
	v_add3_u32 v232, v201, s87, 32
	v_med3_i32 v232, v232, 0, v210
	v_lshl_add_u32 v232, v232, 2, s75
	ds_read_b32 v228, v232 offset:0
	v_add3_u32 v233, v201, s87, 33
	v_med3_i32 v233, v233, 0, v210
	v_lshl_add_u32 v233, v233, 2, s75
	ds_read_b32 v229, v233 offset:0
	ds_read_b64_tr_b16 v[166:167], v186 offset:24576
	ds_read_b64_tr_b16 v[168:169], v187 offset:24832
	v_mfma_f32_16x16x32_bf16 v[20:23], v[96:99], v[170:173], v[20:23]
	v_add3_u32 v234, v201, s87, 34
	v_med3_i32 v234, v234, 0, v210
	v_lshl_add_u32 v234, v234, 2, s75
	ds_read_b32 v230, v234 offset:0
	v_add3_u32 v235, v201, s87, 35
	v_med3_i32 v235, v235, 0, v210
	v_lshl_add_u32 v235, v235, 2, s75
	ds_read_b32 v231, v235 offset:0
	s_waitcnt lgkmcnt(5)
	v_add_f32_e32 v80, v80, v228
	s_waitcnt lgkmcnt(4)
	v_add_f32_e32 v81, v81, v229
	v_mfma_f32_16x16x32_bf16 v[52:55], v[104:107], v[170:173], v[52:55]
	s_waitcnt lgkmcnt(1)
	v_add_f32_e32 v82, v82, v230
	s_waitcnt lgkmcnt(0)
	v_add_f32_e32 v83, v83, v231
	v_add3_u32 v232, v201, s87, 16
	v_med3_i32 v232, v232, 0, v210
	v_lshl_add_u32 v232, v232, 2, s75
	ds_read_b32 v228, v232 offset:0
	v_add3_u32 v233, v201, s87, 17
	v_med3_i32 v233, v233, 0, v210
	v_lshl_add_u32 v233, v233, 2, s75
	ds_read_b32 v229, v233 offset:0
	ds_read_b64_tr_b16 v[170:171], v188 offset:24576
	ds_read_b64_tr_b16 v[172:173], v189 offset:24832
	v_mfma_f32_16x16x32_bf16 v[24:27], v[96:99], v[174:177], v[24:27]
	v_add3_u32 v234, v201, s87, 18
	v_med3_i32 v234, v234, 0, v210
	v_lshl_add_u32 v234, v234, 2, s75
	ds_read_b32 v230, v234 offset:0
	v_add3_u32 v235, v201, s87, 19
	v_med3_i32 v235, v235, 0, v210
	v_lshl_add_u32 v235, v235, 2, s75
	ds_read_b32 v231, v235 offset:0
	s_waitcnt lgkmcnt(5)
	v_add_f32_e32 v84, v84, v228
	s_waitcnt lgkmcnt(4)
	v_add_f32_e32 v85, v85, v229
	v_mfma_f32_16x16x32_bf16 v[56:59], v[104:107], v[174:177], v[56:59]
	s_waitcnt lgkmcnt(1)
	v_add_f32_e32 v86, v86, v230
	s_waitcnt lgkmcnt(0)
	v_add_f32_e32 v87, v87, v231
	v_exp_f32_e32 v80, v80
	v_exp_f32_e32 v81, v81
	ds_read_b64_tr_b16 v[174:175], v186 offset:25088
	ds_read_b64_tr_b16 v[176:177], v187 offset:25344
	v_mfma_f32_16x16x32_bf16 v[28:31], v[96:99], v[178:181], v[28:31]
	v_exp_f32_e32 v82, v82
	v_exp_f32_e32 v83, v83
	v_exp_f32_e32 v84, v84
	v_exp_f32_e32 v85, v85
	v_mfma_f32_16x16x32_bf16 v[60:63], v[104:107], v[178:181], v[60:63]
	v_exp_f32_e32 v86, v86
	v_exp_f32_e32 v87, v87
	v_add3_u32 v232, v201, s87, 36
	v_med3_i32 v232, v232, 0, v210
	v_lshl_add_u32 v232, v232, 2, s75
	ds_read_b32 v228, v232 offset:0
	v_add3_u32 v233, v201, s87, 37
	v_med3_i32 v233, v233, 0, v210
	v_lshl_add_u32 v233, v233, 2, s75
	ds_read_b32 v229, v233 offset:0
	ds_read_b64_tr_b16 v[178:179], v188 offset:25088
	ds_read_b64_tr_b16 v[180:181], v189 offset:25344
	v_mfma_f32_16x16x32_bf16 v[0:3], v[100:103], v[166:169], v[0:3]
	v_add3_u32 v234, v201, s87, 38
	v_med3_i32 v234, v234, 0, v210
	v_lshl_add_u32 v234, v234, 2, s75
	ds_read_b32 v230, v234 offset:0
	v_add3_u32 v235, v201, s87, 39
	v_med3_i32 v235, v235, 0, v210
	v_lshl_add_u32 v235, v235, 2, s75
	ds_read_b32 v231, v235 offset:0
	s_waitcnt lgkmcnt(5)
	v_add_f32_e32 v88, v88, v228
	s_waitcnt lgkmcnt(4)
	v_add_f32_e32 v89, v89, v229
	v_mfma_f32_16x16x32_bf16 v[32:35], v[108:111], v[166:169], v[32:35]
	s_waitcnt lgkmcnt(1)
	v_add_f32_e32 v90, v90, v230
	s_waitcnt lgkmcnt(0)
	v_add_f32_e32 v91, v91, v231
	v_add3_u32 v232, v201, s87, 20
	v_med3_i32 v232, v232, 0, v210
	v_lshl_add_u32 v232, v232, 2, s75
	ds_read_b32 v228, v232 offset:0
	v_add3_u32 v233, v201, s87, 21
	v_med3_i32 v233, v233, 0, v210
	v_lshl_add_u32 v233, v233, 2, s75
	ds_read_b32 v229, v233 offset:0
	v_mfma_f32_16x16x32_bf16 v[244:247], v[100:103], v[236:239], v[244:247]
	v_mfma_f32_16x16x32_bf16 v[248:251], v[108:111], v[236:239], v[248:251]
	ds_read_b64_tr_b16 v[166:167], v186 offset:25600
	ds_read_b64_tr_b16 v[168:169], v187 offset:25856
	v_mfma_f32_16x16x32_bf16 v[4:7], v[100:103], v[170:173], v[4:7]
	v_add3_u32 v234, v201, s87, 22
	v_med3_i32 v234, v234, 0, v210
	v_lshl_add_u32 v234, v234, 2, s75
	ds_read_b32 v230, v234 offset:0
	v_add3_u32 v235, v201, s87, 23
	v_med3_i32 v235, v235, 0, v210
	v_lshl_add_u32 v235, v235, 2, s75
	ds_read_b32 v231, v235 offset:0
	s_waitcnt lgkmcnt(5)
	v_add_f32_e32 v92, v92, v228
	s_waitcnt lgkmcnt(4)
	v_add_f32_e32 v93, v93, v229
	v_mfma_f32_16x16x32_bf16 v[36:39], v[108:111], v[170:173], v[36:39]
	s_waitcnt lgkmcnt(1)
	v_add_f32_e32 v94, v94, v230
	s_waitcnt lgkmcnt(0)
	v_add_f32_e32 v95, v95, v231
	v_exp_f32_e32 v88, v88
	v_exp_f32_e32 v89, v89
	ds_read_b64_tr_b16 v[170:171], v188 offset:25600
	ds_read_b64_tr_b16 v[172:173], v189 offset:25856
	v_mfma_f32_16x16x32_bf16 v[8:11], v[100:103], v[174:177], v[8:11]
	v_exp_f32_e32 v90, v90
	v_exp_f32_e32 v91, v91
	v_exp_f32_e32 v92, v92
	v_exp_f32_e32 v93, v93
	v_mfma_f32_16x16x32_bf16 v[40:43], v[108:111], v[174:177], v[40:43]
	v_exp_f32_e32 v94, v94
	v_exp_f32_e32 v95, v95
	v_cvt_pk_bf16_f32 v216, v80, v81
	v_cvt_pk_bf16_f32 v217, v82, v83
	ds_read_b64_tr_b16 v[174:175], v186 offset:26112
	ds_read_b64_tr_b16 v[176:177], v187 offset:26368
	v_mfma_f32_16x16x32_bf16 v[12:15], v[100:103], v[178:181], v[12:15]
	v_cvt_pk_bf16_f32 v218, v88, v89
	v_cvt_pk_bf16_f32 v219, v90, v91
	v_cvt_pk_bf16_f32 v224, v84, v85
	v_cvt_pk_bf16_f32 v225, v86, v87
	v_mfma_f32_16x16x32_bf16 v[44:47], v[108:111], v[178:181], v[44:47]
	v_cvt_pk_bf16_f32 v226, v92, v93
	v_cvt_pk_bf16_f32 v227, v94, v95
	ds_read_b64_tr_b16 v[178:179], v188 offset:26112
	ds_read_b64_tr_b16 v[180:181], v189 offset:26368
	s_waitcnt vmcnt(0) lgkmcnt(0)
	s_barrier
.La_done0:
	s_add_i32 s95, s95, 1
	s_add_i32 s0, s95, 1
	s_cmp_lg_u32 s0, s12
	s_cbranch_scc1 .La_c1_p1
	v_sub_f32_e32 v142, 0, v195
	v_mov_b32_e32 v143, v142
	v_mov_b32_e32 v144, v142
	v_mov_b32_e32 v145, v142
	v_sub_f32_e32 v146, 0, v196
	v_mov_b32_e32 v147, v146
	v_mov_b32_e32 v148, v146
	v_mov_b32_e32 v149, v146

.La_c3_p1:
	s_add_i32 s87, s87, 64
	s_sub_u32 s0, s0, s12
	s_cmp_lt_u32 s0, s13
	s_cbranch_scc1 .La_band1
	ds_read_b128 v[150:153], v184 offset:0
	ds_read_b128 v[154:157], v185 offset:0
	ds_read_b128 v[158:161], v184 offset:2048
	s_add_i32 s1, s94, 0xfffe0000
	v_mfma_f32_16x16x32_bf16 v[16:19], v[100:103], v[166:169], v[16:19]
	s_mov_b32 m0, s89
	s_nop 0
	buffer_load_dwordx4 v190, s[16:19], s94 offen lds
	v_mfma_f32_16x16x32_bf16 v[48:51], v[108:111], v[166:169], v[48:51]
	s_mov_b32 m0, s90
	s_nop 0
	buffer_load_dwordx4 v191, s[60:63], s1 offen lds
	v_mfma_f32_16x16x32_bf16 v[20:23], v[100:103], v[170:173], v[20:23]
	s_mov_b32 m0, s91
	s_nop 0
	buffer_load_dwordx4 v192, s[60:63], s1 offen lds
	v_mfma_f32_16x16x32_bf16 v[52:55], v[108:111], v[170:173], v[52:55]
	v_mfma_f32_16x16x32_bf16 v[24:27], v[100:103], v[174:177], v[24:27]
	v_mfma_f32_16x16x32_bf16 v[56:59], v[108:111], v[174:177], v[56:59]
	v_mfma_f32_16x16x32_bf16 v[28:31], v[100:103], v[178:181], v[28:31]
	v_mfma_f32_16x16x32_bf16 v[60:63], v[108:111], v[178:181], v[60:63]
	s_add_i32 s94, s94, 0x20000
	ds_read_b128 v[162:165], v185 offset:2048
	s_waitcnt lgkmcnt(3)
	v_mfma_f32_16x16x32_bf16 v[64:67], v[150:153], v[112:115], v[142:145]
	v_mfma_f32_16x16x32_bf16 v[68:71], v[150:153], v[120:123], v[146:149]
	ds_read_b128 v[150:153], v184 offset:4096
	s_waitcnt lgkmcnt(3)
	v_mfma_f32_16x16x32_bf16 v[64:67], v[154:157], v[116:119], v[64:67]
	v_mfma_f32_16x16x32_bf16 v[68:71], v[154:157], v[124:127], v[68:71]
	ds_read_b128 v[154:157], v185 offset:4096
	s_waitcnt lgkmcnt(3)
	v_mfma_f32_16x16x32_bf16 v[72:75], v[158:161], v[112:115], v[142:145]
	v_mfma_f32_16x16x32_bf16 v[76:79], v[158:161], v[120:123], v[146:149]
	ds_read_b128 v[158:161], v184 offset:6144
	s_waitcnt lgkmcnt(3)
	v_mfma_f32_16x16x32_bf16 v[72:75], v[162:165], v[116:119], v[72:75]
	v_mfma_f32_16x16x32_bf16 v[76:79], v[162:165], v[124:127], v[76:79]
	v_exp_f32_e32 v64, v64
	v_exp_f32_e32 v65, v65
	ds_read_b128 v[162:165], v185 offset:6144
	s_waitcnt lgkmcnt(3)
	v_mfma_f32_16x16x32_bf16 v[80:83], v[150:153], v[112:115], v[142:145]
	v_exp_f32_e32 v66, v66
	v_exp_f32_e32 v67, v67
	v_mfma_f32_16x16x32_bf16 v[84:87], v[150:153], v[120:123], v[146:149]
	v_exp_f32_e32 v68, v68
	v_exp_f32_e32 v69, v69
	ds_read_b64_tr_b16 v[166:167], v186 offset:32768
	ds_read_b64_tr_b16 v[168:169], v187 offset:33024
	s_waitcnt lgkmcnt(4)
	v_mfma_f32_16x16x32_bf16 v[80:83], v[154:157], v[116:119], v[80:83]
	v_exp_f32_e32 v70, v70
	v_exp_f32_e32 v71, v71
	v_mfma_f32_16x16x32_bf16 v[84:87], v[154:157], v[124:127], v[84:87]
	v_exp_f32_e32 v72, v72
	v_exp_f32_e32 v73, v73
	ds_read_b64_tr_b16 v[170:171], v188 offset:32768
	ds_read_b64_tr_b16 v[172:173], v189 offset:33024
	s_waitcnt lgkmcnt(5)
	v_mfma_f32_16x16x32_bf16 v[88:91], v[158:161], v[112:115], v[142:145]
	v_exp_f32_e32 v74, v74
	v_exp_f32_e32 v75, v75
	v_mfma_f32_16x16x32_bf16 v[92:95], v[158:161], v[120:123], v[146:149]
	v_exp_f32_e32 v76, v76
	v_exp_f32_e32 v77, v77
	ds_read_b64_tr_b16 v[174:175], v186 offset:33280
	ds_read_b64_tr_b16 v[176:177], v187 offset:33536
	s_waitcnt lgkmcnt(6)
	v_mfma_f32_16x16x32_bf16 v[88:91], v[162:165], v[116:119], v[88:91]
	v_exp_f32_e32 v78, v78
	v_exp_f32_e32 v79, v79
	v_mfma_f32_16x16x32_bf16 v[92:95], v[162:165], v[124:127], v[92:95]
	v_cvt_pk_bf16_f32 v96, v64, v65
	v_cvt_pk_bf16_f32 v97, v66, v67
	ds_read_b64_tr_b16 v[178:179], v188 offset:33280
	ds_read_b64_tr_b16 v[180:181], v189 offset:33536
	s_waitcnt lgkmcnt(6)
	v_mfma_f32_16x16x32_bf16 v[0:3], v[212:215], v[166:169], v[0:3]
	v_cvt_pk_bf16_f32 v98, v72, v73
	v_cvt_pk_bf16_f32 v99, v74, v75
	v_mfma_f32_16x16x32_bf16 v[32:35], v[220:223], v[166:169], v[32:35]
	v_cvt_pk_bf16_f32 v104, v68, v69
	v_cvt_pk_bf16_f32 v105, v70, v71
	v_mfma_f32_16x16x32_bf16 v[244:247], v[212:215], v[236:239], v[244:247]
	v_mfma_f32_16x16x32_bf16 v[248:251], v[220:223], v[236:239], v[248:251]
	ds_read_b64_tr_b16 v[166:167], v186 offset:33792
	ds_read_b64_tr_b16 v[168:169], v187 offset:34048
	s_waitcnt lgkmcnt(6)
	v_mfma_f32_16x16x32_bf16 v[4:7], v[212:215], v[170:173], v[4:7]
	v_cvt_pk_bf16_f32 v106, v76, v77
	v_cvt_pk_bf16_f32 v107, v78, v79
	v_mfma_f32_16x16x32_bf16 v[36:39], v[220:223], v[170:173], v[36:39]
	v_exp_f32_e32 v80, v80
	v_exp_f32_e32 v81, v81
	ds_read_b64_tr_b16 v[170:171], v188 offset:33792
	ds_read_b64_tr_b16 v[172:173], v189 offset:34048
	s_waitcnt lgkmcnt(6)
	v_mfma_f32_16x16x32_bf16 v[8:11], v[212:215], v[174:177], v[8:11]
	v_exp_f32_e32 v82, v82
	v_exp_f32_e32 v83, v83
	v_mfma_f32_16x16x32_bf16 v[40:43], v[220:223], v[174:177], v[40:43]
	v_exp_f32_e32 v84, v84
	v_exp_f32_e32 v85, v85
	ds_read_b64_tr_b16 v[174:175], v186 offset:34304
	ds_read_b64_tr_b16 v[176:177], v187 offset:34560
	s_waitcnt lgkmcnt(6)
	v_mfma_f32_16x16x32_bf16 v[12:15], v[212:215], v[178:181], v[12:15]
	v_exp_f32_e32 v86, v86
	v_exp_f32_e32 v87, v87
	v_mfma_f32_16x16x32_bf16 v[44:47], v[220:223], v[178:181], v[44:47]
	v_exp_f32_e32 v88, v88
	v_exp_f32_e32 v89, v89
	ds_read_b64_tr_b16 v[178:179], v188 offset:34304
	ds_read_b64_tr_b16 v[180:181], v189 offset:34560
	s_waitcnt lgkmcnt(6)
	v_mfma_f32_16x16x32_bf16 v[16:19], v[212:215], v[166:169], v[16:19]
	v_exp_f32_e32 v90, v90
	v_exp_f32_e32 v91, v91
	v_mfma_f32_16x16x32_bf16 v[48:51], v[220:223], v[166:169], v[48:51]
	v_exp_f32_e32 v92, v92
	v_exp_f32_e32 v93, v93
	ds_read_b64_tr_b16 v[166:167], v186 offset:40960
	ds_read_b64_tr_b16 v[168:169], v187 offset:41216
	s_waitcnt lgkmcnt(6)
	v_mfma_f32_16x16x32_bf16 v[20:23], v[212:215], v[170:173], v[20:23]
	v_exp_f32_e32 v94, v94
	v_exp_f32_e32 v95, v95
	v_mfma_f32_16x16x32_bf16 v[52:55], v[220:223], v[170:173], v[52:55]
	v_cvt_pk_bf16_f32 v100, v80, v81
	v_cvt_pk_bf16_f32 v101, v82, v83
	ds_read_b64_tr_b16 v[170:171], v188 offset:40960
	ds_read_b64_tr_b16 v[172:173], v189 offset:41216
	s_waitcnt lgkmcnt(6)
	v_mfma_f32_16x16x32_bf16 v[24:27], v[212:215], v[174:177], v[24:27]
	v_cvt_pk_bf16_f32 v102, v88, v89
	v_cvt_pk_bf16_f32 v103, v90, v91
	v_mfma_f32_16x16x32_bf16 v[56:59], v[220:223], v[174:177], v[56:59]
	v_cvt_pk_bf16_f32 v108, v84, v85
	v_cvt_pk_bf16_f32 v109, v86, v87
	ds_read_b64_tr_b16 v[174:175], v186 offset:41472
	ds_read_b64_tr_b16 v[176:177], v187 offset:41728
	s_waitcnt lgkmcnt(6)
	v_mfma_f32_16x16x32_bf16 v[28:31], v[212:215], v[178:181], v[28:31]
	v_cvt_pk_bf16_f32 v110, v92, v93
	v_cvt_pk_bf16_f32 v111, v94, v95
	v_mfma_f32_16x16x32_bf16 v[60:63], v[220:223], v[178:181], v[60:63]
	ds_read_b64_tr_b16 v[178:179], v188 offset:41472
	ds_read_b64_tr_b16 v[180:181], v189 offset:41728
	s_waitcnt lgkmcnt(6)
	v_mfma_f32_16x16x32_bf16 v[0:3], v[216:219], v[166:169], v[0:3]
	v_mfma_f32_16x16x32_bf16 v[32:35], v[224:227], v[166:169], v[32:35]
	v_mfma_f32_16x16x32_bf16 v[244:247], v[216:219], v[236:239], v[244:247]
	v_mfma_f32_16x16x32_bf16 v[248:251], v[224:227], v[236:239], v[248:251]
	ds_read_b64_tr_b16 v[166:167], v186 offset:41984
	ds_read_b64_tr_b16 v[168:169], v187 offset:42240
	s_waitcnt lgkmcnt(6)
	v_mfma_f32_16x16x32_bf16 v[4:7], v[216:219], v[170:173], v[4:7]
	v_mfma_f32_16x16x32_bf16 v[36:39], v[224:227], v[170:173], v[36:39]
	ds_read_b64_tr_b16 v[170:171], v188 offset:41984
	ds_read_b64_tr_b16 v[172:173], v189 offset:42240
	s_waitcnt lgkmcnt(6)
	v_mfma_f32_16x16x32_bf16 v[8:11], v[216:219], v[174:177], v[8:11]
	v_mfma_f32_16x16x32_bf16 v[40:43], v[224:227], v[174:177], v[40:43]
	ds_read_b64_tr_b16 v[174:175], v186 offset:42496
	ds_read_b64_tr_b16 v[176:177], v187 offset:42752
	s_waitcnt lgkmcnt(6)
	v_mfma_f32_16x16x32_bf16 v[12:15], v[216:219], v[178:181], v[12:15]
	v_mfma_f32_16x16x32_bf16 v[44:47], v[224:227], v[178:181], v[44:47]
	ds_read_b64_tr_b16 v[178:179], v188 offset:42496
	ds_read_b64_tr_b16 v[180:181], v189 offset:42752
	s_waitcnt vmcnt(0) lgkmcnt(0)
	s_barrier
	s_branch .La_done1
.La_band1:
	ds_read_b128 v[150:153], v184 offset:0
	ds_read_b128 v[154:157], v185 offset:0
	ds_read_b128 v[158:161], v184 offset:2048
	s_add_i32 s1, s94, 0xfffe0000
	v_mfma_f32_16x16x32_bf16 v[16:19], v[100:103], v[166:169], v[16:19]
	s_mov_b32 m0, s89
	s_nop 0
	buffer_load_dwordx4 v190, s[16:19], s94 offen lds
	v_mfma_f32_16x16x32_bf16 v[48:51], v[108:111], v[166:169], v[48:51]
	s_mov_b32 m0, s90
	s_nop 0
	buffer_load_dwordx4 v191, s[60:63], s1 offen lds
	v_mfma_f32_16x16x32_bf16 v[20:23], v[100:103], v[170:173], v[20:23]
	s_mov_b32 m0, s91
	s_nop 0
	buffer_load_dwordx4 v192, s[60:63], s1 offen lds
	v_mfma_f32_16x16x32_bf16 v[52:55], v[108:111], v[170:173], v[52:55]
	v_mfma_f32_16x16x32_bf16 v[24:27], v[100:103], v[174:177], v[24:27]
	v_mfma_f32_16x16x32_bf16 v[56:59], v[108:111], v[174:177], v[56:59]
	v_mfma_f32_16x16x32_bf16 v[28:31], v[100:103], v[178:181], v[28:31]
	v_mfma_f32_16x16x32_bf16 v[60:63], v[108:111], v[178:181], v[60:63]
	s_add_i32 s94, s94, 0x20000
	ds_read_b128 v[162:165], v185 offset:2048
	s_waitcnt lgkmcnt(3)
	v_mfma_f32_16x16x32_bf16 v[64:67], v[150:153], v[112:115], v[142:145]
	v_mfma_f32_16x16x32_bf16 v[68:71], v[150:153], v[120:123], v[146:149]
	ds_read_b128 v[150:153], v184 offset:4096
	s_waitcnt lgkmcnt(3)
	v_mfma_f32_16x16x32_bf16 v[64:67], v[154:157], v[116:119], v[64:67]
	v_mfma_f32_16x16x32_bf16 v[68:71], v[154:157], v[124:127], v[68:71]
	ds_read_b128 v[154:157], v185 offset:4096
	s_waitcnt lgkmcnt(3)
	v_mfma_f32_16x16x32_bf16 v[72:75], v[158:161], v[112:115], v[142:145]
	v_mfma_f32_16x16x32_bf16 v[76:79], v[158:161], v[120:123], v[146:149]
	ds_read_b128 v[158:161], v184 offset:6144
	s_waitcnt lgkmcnt(3)
	v_mfma_f32_16x16x32_bf16 v[72:75], v[162:165], v[116:119], v[72:75]
	v_mfma_f32_16x16x32_bf16 v[76:79], v[162:165], v[124:127], v[76:79]
	v_add3_u32 v232, v201, s87, 0
	v_med3_i32 v232, v232, 0, v210
	v_lshl_add_u32 v232, v232, 2, s75
	ds_read_b32 v228, v232 offset:0
	v_add3_u32 v233, v201, s87, 1
	v_med3_i32 v233, v233, 0, v210
	v_lshl_add_u32 v233, v233, 2, s75
	ds_read_b32 v229, v233 offset:0
	ds_read_b128 v[162:165], v185 offset:6144
	s_waitcnt lgkmcnt(5)
	v_mfma_f32_16x16x32_bf16 v[80:83], v[150:153], v[112:115], v[142:145]
	v_add3_u32 v234, v201, s87, 2
	v_med3_i32 v234, v234, 0, v210
	v_lshl_add_u32 v234, v234, 2, s75
	ds_read_b32 v230, v234 offset:0
	v_add3_u32 v235, v201, s87, 3
	v_med3_i32 v235, v235, 0, v210
	v_lshl_add_u32 v235, v235, 2, s75
	ds_read_b32 v231, v235 offset:0
	v_mfma_f32_16x16x32_bf16 v[84:87], v[150:153], v[120:123], v[146:149]
	s_waitcnt lgkmcnt(4)
	v_add_f32_e32 v64, v64, v228
	s_waitcnt lgkmcnt(3)
	v_add_f32_e32 v65, v65, v229
	ds_read_b64_tr_b16 v[166:167], v186 offset:32768
	ds_read_b64_tr_b16 v[168:169], v187 offset:33024
	v_mfma_f32_16x16x32_bf16 v[80:83], v[154:157], v[116:119], v[80:83]
	s_waitcnt lgkmcnt(3)
	v_add_f32_e32 v66, v66, v230
	s_waitcnt lgkmcnt(2)
	v_add_f32_e32 v67, v67, v231
	v_mfma_f32_16x16x32_bf16 v[84:87], v[154:157], v[124:127], v[84:87]
	v_add3_u32 v232, v201, s87, -16
	v_med3_i32 v232, v232, 0, v210
	v_lshl_add_u32 v232, v232, 2, s75
	ds_read_b32 v228, v232 offset:0
	v_add3_u32 v233, v201, s87, -15
	v_med3_i32 v233, v233, 0, v210
	v_lshl_add_u32 v233, v233, 2, s75
	ds_read_b32 v229, v233 offset:0
	ds_read_b64_tr_b16 v[170:171], v188 offset:32768
	ds_read_b64_tr_b16 v[172:173], v189 offset:33024
	v_mfma_f32_16x16x32_bf16 v[88:91], v[158:161], v[112:115], v[142:145]
	v_add3_u32 v234, v201, s87, -14
	v_med3_i32 v234, v234, 0, v210
	v_lshl_add_u32 v234, v234, 2, s75
	ds_read_b32 v230, v234 offset:0
	v_add3_u32 v235, v201, s87, -13
	v_med3_i32 v235, v235, 0, v210
	v_lshl_add_u32 v235, v235, 2, s75
	ds_read_b32 v231, v235 offset:0
	v_mfma_f32_16x16x32_bf16 v[92:95], v[158:161], v[120:123], v[146:149]
	s_waitcnt lgkmcnt(5)
	v_add_f32_e32 v68, v68, v228
	s_waitcnt lgkmcnt(4)
	v_add_f32_e32 v69, v69, v229
	ds_read_b64_tr_b16 v[174:175], v186 offset:33280
	ds_read_b64_tr_b16 v[176:177], v187 offset:33536
	v_mfma_f32_16x16x32_bf16 v[88:91], v[162:165], v[116:119], v[88:91]
	s_waitcnt lgkmcnt(3)
	v_add_f32_e32 v70, v70, v230
	s_waitcnt lgkmcnt(2)
	v_add_f32_e32 v71, v71, v231
	v_mfma_f32_16x16x32_bf16 v[92:95], v[162:165], v[124:127], v[92:95]
	v_exp_f32_e32 v64, v64
	v_exp_f32_e32 v65, v65
	ds_read_b64_tr_b16 v[178:179], v188 offset:33280
	ds_read_b64_tr_b16 v[180:181], v189 offset:33536
	v_mfma_f32_16x16x32_bf16 v[0:3], v[212:215], v[166:169], v[0:3]
	v_exp_f32_e32 v66, v66
	v_exp_f32_e32 v67, v67
	v_exp_f32_e32 v68, v68
	v_exp_f32_e32 v69, v69
	v_mfma_f32_16x16x32_bf16 v[32:35], v[220:223], v[166:169], v[32:35]
	v_exp_f32_e32 v70, v70
	v_exp_f32_e32 v71, v71
	v_add3_u32 v232, v201, s87, 4
	v_med3_i32 v232, v232, 0, v210
	v_lshl_add_u32 v232, v232, 2, s75
	ds_read_b32 v228, v232 offset:0
	v_add3_u32 v233, v201, s87, 5
	v_med3_i32 v233, v233, 0, v210
	v_lshl_add_u32 v233, v233, 2, s75
	ds_read_b32 v229, v233 offset:0
	v_mfma_f32_16x16x32_bf16 v[244:247], v[212:215], v[236:239], v[244:247]
	v_mfma_f32_16x16x32_bf16 v[248:251], v[220:223], v[236:239], v[248:251]
	ds_read_b64_tr_b16 v[166:167], v186 offset:33792
	ds_read_b64_tr_b16 v[168:169], v187 offset:34048
	v_mfma_f32_16x16x32_bf16 v[4:7], v[212:215], v[170:173], v[4:7]
	v_add3_u32 v234, v201, s87, 6
	v_med3_i32 v234, v234, 0, v210
	v_lshl_add_u32 v234, v234, 2, s75
	ds_read_b32 v230, v234 offset:0
	v_add3_u32 v235, v201, s87, 7
	v_med3_i32 v235, v235, 0, v210
	v_lshl_add_u32 v235, v235, 2, s75
	ds_read_b32 v231, v235 offset:0
	s_waitcnt lgkmcnt(5)
	v_add_f32_e32 v72, v72, v228
	s_waitcnt lgkmcnt(4)
	v_add_f32_e32 v73, v73, v229
	v_mfma_f32_16x16x32_bf16 v[36:39], v[220:223], v[170:173], v[36:39]
	s_waitcnt lgkmcnt(1)
	v_add_f32_e32 v74, v74, v230
	s_waitcnt lgkmcnt(0)
	v_add_f32_e32 v75, v75, v231
	v_add3_u32 v232, v201, s87, -12
	v_med3_i32 v232, v232, 0, v210
	v_lshl_add_u32 v232, v232, 2, s75
	ds_read_b32 v228, v232 offset:0
	v_add3_u32 v233, v201, s87, -11
	v_med3_i32 v233, v233, 0, v210
	v_lshl_add_u32 v233, v233, 2, s75
	ds_read_b32 v229, v233 offset:0
	ds_read_b64_tr_b16 v[170:171], v188 offset:33792
	ds_read_b64_tr_b16 v[172:173], v189 offset:34048
	v_mfma_f32_16x16x32_bf16 v[8:11], v[212:215], v[174:177], v[8:11]
	v_add3_u32 v234, v201, s87, -10
	v_med3_i32 v234, v234, 0, v210
	v_lshl_add_u32 v234, v234, 2, s75
	ds_read_b32 v230, v234 offset:0
	v_add3_u32 v235, v201, s87, -9
	v_med3_i32 v235, v235, 0, v210
	v_lshl_add_u32 v235, v235, 2, s75
	ds_read_b32 v231, v235 offset:0
	s_waitcnt lgkmcnt(5)
	v_add_f32_e32 v76, v76, v228
	s_waitcnt lgkmcnt(4)
	v_add_f32_e32 v77, v77, v229
	v_mfma_f32_16x16x32_bf16 v[40:43], v[220:223], v[174:177], v[40:43]
	s_waitcnt lgkmcnt(1)
	v_add_f32_e32 v78, v78, v230
	s_waitcnt lgkmcnt(0)
	v_add_f32_e32 v79, v79, v231
	v_exp_f32_e32 v72, v72
	v_exp_f32_e32 v73, v73
	ds_read_b64_tr_b16 v[174:175], v186 offset:34304
	ds_read_b64_tr_b16 v[176:177], v187 offset:34560
	v_mfma_f32_16x16x32_bf16 v[12:15], v[212:215], v[178:181], v[12:15]
	v_exp_f32_e32 v74, v74
	v_exp_f32_e32 v75, v75
	v_exp_f32_e32 v76, v76
	v_exp_f32_e32 v77, v77
	v_mfma_f32_16x16x32_bf16 v[44:47], v[220:223], v[178:181], v[44:47]
	v_exp_f32_e32 v78, v78
	v_exp_f32_e32 v79, v79
	v_cvt_pk_bf16_f32 v96, v64, v65
	v_cvt_pk_bf16_f32 v97, v66, v67
	ds_read_b64_tr_b16 v[178:179], v188 offset:34304
	ds_read_b64_tr_b16 v[180:181], v189 offset:34560
	v_mfma_f32_16x16x32_bf16 v[16:19], v[212:215], v[166:169], v[16:19]
	v_cvt_pk_bf16_f32 v98, v72, v73
	v_cvt_pk_bf16_f32 v99, v74, v75
	v_cvt_pk_bf16_f32 v104, v68, v69
	v_cvt_pk_bf16_f32 v105, v70, v71
	v_mfma_f32_16x16x32_bf16 v[48:51], v[220:223], v[166:169], v[48:51]
	v_cvt_pk_bf16_f32 v106, v76, v77
	v_cvt_pk_bf16_f32 v107, v78, v79
	v_add3_u32 v232, v201, s87, 32
	v_med3_i32 v232, v232, 0, v210
	v_lshl_add_u32 v232, v232, 2, s75
	ds_read_b32 v228, v232 offset:0
	v_add3_u32 v233, v201, s87, 33
	v_med3_i32 v233, v233, 0, v210
	v_lshl_add_u32 v233, v233, 2, s75
	ds_read_b32 v229, v233 offset:0
	ds_read_b64_tr_b16 v[166:167], v186 offset:40960
	ds_read_b64_tr_b16 v[168:169], v187 offset:41216
	v_mfma_f32_16x16x32_bf16 v[20:23], v[212:215], v[170:173], v[20:23]
	v_add3_u32 v234, v201, s87, 34
	v_med3_i32 v234, v234, 0, v210
	v_lshl_add_u32 v234, v234, 2, s75
	ds_read_b32 v230, v234 offset:0
	v_add3_u32 v235, v201, s87, 35
	v_med3_i32 v235, v235, 0, v210
	v_lshl_add_u32 v235, v235, 2, s75
	ds_read_b32 v231, v235 offset:0
	s_waitcnt lgkmcnt(5)
	v_add_f32_e32 v80, v80, v228
	s_waitcnt lgkmcnt(4)
	v_add_f32_e32 v81, v81, v229
	v_mfma_f32_16x16x32_bf16 v[52:55], v[220:223], v[170:173], v[52:55]
	s_waitcnt lgkmcnt(1)
	v_add_f32_e32 v82, v82, v230
	s_waitcnt lgkmcnt(0)
	v_add_f32_e32 v83, v83, v231
	v_add3_u32 v232, v201, s87, 16
	v_med3_i32 v232, v232, 0, v210
	v_lshl_add_u32 v232, v232, 2, s75
	ds_read_b32 v228, v232 offset:0
	v_add3_u32 v233, v201, s87, 17
	v_med3_i32 v233, v233, 0, v210
	v_lshl_add_u32 v233, v233, 2, s75
	ds_read_b32 v229, v233 offset:0
	ds_read_b64_tr_b16 v[170:171], v188 offset:40960
	ds_read_b64_tr_b16 v[172:173], v189 offset:41216
	v_mfma_f32_16x16x32_bf16 v[24:27], v[212:215], v[174:177], v[24:27]
	v_add3_u32 v234, v201, s87, 18
	v_med3_i32 v234, v234, 0, v210
	v_lshl_add_u32 v234, v234, 2, s75
	ds_read_b32 v230, v234 offset:0
	v_add3_u32 v235, v201, s87, 19
	v_med3_i32 v235, v235, 0, v210
	v_lshl_add_u32 v235, v235, 2, s75
	ds_read_b32 v231, v235 offset:0
	s_waitcnt lgkmcnt(5)
	v_add_f32_e32 v84, v84, v228
	s_waitcnt lgkmcnt(4)
	v_add_f32_e32 v85, v85, v229
	v_mfma_f32_16x16x32_bf16 v[56:59], v[220:223], v[174:177], v[56:59]
	s_waitcnt lgkmcnt(1)
	v_add_f32_e32 v86, v86, v230
	s_waitcnt lgkmcnt(0)
	v_add_f32_e32 v87, v87, v231
	v_exp_f32_e32 v80, v80
	v_exp_f32_e32 v81, v81
	ds_read_b64_tr_b16 v[174:175], v186 offset:41472
	ds_read_b64_tr_b16 v[176:177], v187 offset:41728
	v_mfma_f32_16x16x32_bf16 v[28:31], v[212:215], v[178:181], v[28:31]
	v_exp_f32_e32 v82, v82
	v_exp_f32_e32 v83, v83
	v_exp_f32_e32 v84, v84
	v_exp_f32_e32 v85, v85
	v_mfma_f32_16x16x32_bf16 v[60:63], v[220:223], v[178:181], v[60:63]
	v_exp_f32_e32 v86, v86
	v_exp_f32_e32 v87, v87
	v_add3_u32 v232, v201, s87, 36
	v_med3_i32 v232, v232, 0, v210
	v_lshl_add_u32 v232, v232, 2, s75
	ds_read_b32 v228, v232 offset:0
	v_add3_u32 v233, v201, s87, 37
	v_med3_i32 v233, v233, 0, v210
	v_lshl_add_u32 v233, v233, 2, s75
	ds_read_b32 v229, v233 offset:0
	ds_read_b64_tr_b16 v[178:179], v188 offset:41472
	ds_read_b64_tr_b16 v[180:181], v189 offset:41728
	v_mfma_f32_16x16x32_bf16 v[0:3], v[216:219], v[166:169], v[0:3]
	v_add3_u32 v234, v201, s87, 38
	v_med3_i32 v234, v234, 0, v210
	v_lshl_add_u32 v234, v234, 2, s75
	ds_read_b32 v230, v234 offset:0
	v_add3_u32 v235, v201, s87, 39
	v_med3_i32 v235, v235, 0, v210
	v_lshl_add_u32 v235, v235, 2, s75
	ds_read_b32 v231, v235 offset:0
	s_waitcnt lgkmcnt(5)
	v_add_f32_e32 v88, v88, v228
	s_waitcnt lgkmcnt(4)
	v_add_f32_e32 v89, v89, v229
	v_mfma_f32_16x16x32_bf16 v[32:35], v[224:227], v[166:169], v[32:35]
	s_waitcnt lgkmcnt(1)
	v_add_f32_e32 v90, v90, v230
	s_waitcnt lgkmcnt(0)
	v_add_f32_e32 v91, v91, v231
	v_add3_u32 v232, v201, s87, 20
	v_med3_i32 v232, v232, 0, v210
	v_lshl_add_u32 v232, v232, 2, s75
	ds_read_b32 v228, v232 offset:0
	v_add3_u32 v233, v201, s87, 21
	v_med3_i32 v233, v233, 0, v210
	v_lshl_add_u32 v233, v233, 2, s75
	ds_read_b32 v229, v233 offset:0
	v_mfma_f32_16x16x32_bf16 v[244:247], v[216:219], v[236:239], v[244:247]
	v_mfma_f32_16x16x32_bf16 v[248:251], v[224:227], v[236:239], v[248:251]
	ds_read_b64_tr_b16 v[166:167], v186 offset:41984
	ds_read_b64_tr_b16 v[168:169], v187 offset:42240
	v_mfma_f32_16x16x32_bf16 v[4:7], v[216:219], v[170:173], v[4:7]
	v_add3_u32 v234, v201, s87, 22
	v_med3_i32 v234, v234, 0, v210
	v_lshl_add_u32 v234, v234, 2, s75
	ds_read_b32 v230, v234 offset:0
	v_add3_u32 v235, v201, s87, 23
	v_med3_i32 v235, v235, 0, v210
	v_lshl_add_u32 v235, v235, 2, s75
	ds_read_b32 v231, v235 offset:0
	s_waitcnt lgkmcnt(5)
	v_add_f32_e32 v92, v92, v228
	s_waitcnt lgkmcnt(4)
	v_add_f32_e32 v93, v93, v229
	v_mfma_f32_16x16x32_bf16 v[36:39], v[224:227], v[170:173], v[36:39]
	s_waitcnt lgkmcnt(1)
	v_add_f32_e32 v94, v94, v230
	s_waitcnt lgkmcnt(0)
	v_add_f32_e32 v95, v95, v231
	v_exp_f32_e32 v88, v88
	v_exp_f32_e32 v89, v89
	ds_read_b64_tr_b16 v[170:171], v188 offset:41984
	ds_read_b64_tr_b16 v[172:173], v189 offset:42240
	v_mfma_f32_16x16x32_bf16 v[8:11], v[216:219], v[174:177], v[8:11]
	v_exp_f32_e32 v90, v90
	v_exp_f32_e32 v91, v91
	v_exp_f32_e32 v92, v92
	v_exp_f32_e32 v93, v93
	v_mfma_f32_16x16x32_bf16 v[40:43], v[224:227], v[174:177], v[40:43]
	v_exp_f32_e32 v94, v94
	v_exp_f32_e32 v95, v95
	v_cvt_pk_bf16_f32 v100, v80, v81
	v_cvt_pk_bf16_f32 v101, v82, v83
	ds_read_b64_tr_b16 v[174:175], v186 offset:42496
	ds_read_b64_tr_b16 v[176:177], v187 offset:42752
	v_mfma_f32_16x16x32_bf16 v[12:15], v[216:219], v[178:181], v[12:15]
	v_cvt_pk_bf16_f32 v102, v88, v89
	v_cvt_pk_bf16_f32 v103, v90, v91
	v_cvt_pk_bf16_f32 v108, v84, v85
	v_cvt_pk_bf16_f32 v109, v86, v87
	v_mfma_f32_16x16x32_bf16 v[44:47], v[224:227], v[178:181], v[44:47]
	v_cvt_pk_bf16_f32 v110, v92, v93
	v_cvt_pk_bf16_f32 v111, v94, v95
	ds_read_b64_tr_b16 v[178:179], v188 offset:42496
	ds_read_b64_tr_b16 v[180:181], v189 offset:42752
	s_waitcnt vmcnt(0) lgkmcnt(0)
	s_barrier
.La_done1:
	s_add_i32 s95, s95, 1
	s_cmpk_lt_u32 s95, 256
	s_cbranch_scc1 .La_loop
	v_mfma_f32_16x16x32_bf16 v[16:19], v[216:219], v[166:169], v[16:19]
	v_mfma_f32_16x16x32_bf16 v[48:51], v[224:227], v[166:169], v[48:51]
	v_mfma_f32_16x16x32_bf16 v[20:23], v[216:219], v[170:173], v[20:23]
	v_mfma_f32_16x16x32_bf16 v[52:55], v[224:227], v[170:173], v[52:55]
	v_mfma_f32_16x16x32_bf16 v[24:27], v[216:219], v[174:177], v[24:27]
	v_mfma_f32_16x16x32_bf16 v[56:59], v[224:227], v[174:177], v[56:59]
	v_mfma_f32_16x16x32_bf16 v[28:31], v[216:219], v[178:181], v[28:31]
	v_mfma_f32_16x16x32_bf16 v[60:63], v[224:227], v[178:181], v[60:63]
	s_nop 7
	v_rcp_f32_e32 v228, v244
	v_rcp_f32_e32 v229, v245
	v_rcp_f32_e32 v230, v246
	v_rcp_f32_e32 v231, v247
	v_rcp_f32_e32 v232, v248
	v_rcp_f32_e32 v233, v249
	v_rcp_f32_e32 v234, v250
	v_rcp_f32_e32 v235, v251
	s_nop 0
	v_add_u32_e32 v240, 0, v200
	v_mul_f32_e32 v0, v0, v228
	global_store_dword v240, v0, s[98:99] offset:0
	v_mul_f32_e32 v4, v4, v228
	global_store_dword v240, v4, s[98:99] offset:64
	v_mul_f32_e32 v8, v8, v228
	global_store_dword v240, v8, s[98:99] offset:128
	v_mul_f32_e32 v12, v12, v228
	global_store_dword v240, v12, s[98:99] offset:192
	v_mul_f32_e32 v16, v16, v228
	global_store_dword v240, v16, s[98:99] offset:256
	v_mul_f32_e32 v20, v20, v228
	global_store_dword v240, v20, s[98:99] offset:320
	v_mul_f32_e32 v24, v24, v228
	global_store_dword v240, v24, s[98:99] offset:384
	v_mul_f32_e32 v28, v28, v228
	global_store_dword v240, v28, s[98:99] offset:448
	v_add_u32_e32 v240, 512, v200
	v_mul_f32_e32 v1, v1, v229
	global_store_dword v240, v1, s[98:99] offset:0
	v_mul_f32_e32 v5, v5, v229
	global_store_dword v240, v5, s[98:99] offset:64
	v_mul_f32_e32 v9, v9, v229
	global_store_dword v240, v9, s[98:99] offset:128
	v_mul_f32_e32 v13, v13, v229
	global_store_dword v240, v13, s[98:99] offset:192
	v_mul_f32_e32 v17, v17, v229
	global_store_dword v240, v17, s[98:99] offset:256
	v_mul_f32_e32 v21, v21, v229
	global_store_dword v240, v21, s[98:99] offset:320
	v_mul_f32_e32 v25, v25, v229
	global_store_dword v240, v25, s[98:99] offset:384
	v_mul_f32_e32 v29, v29, v229
	global_store_dword v240, v29, s[98:99] offset:448
	v_add_u32_e32 v240, 1024, v200
	v_mul_f32_e32 v2, v2, v230
	global_store_dword v240, v2, s[98:99] offset:0
	v_mul_f32_e32 v6, v6, v230
	global_store_dword v240, v6, s[98:99] offset:64
	v_mul_f32_e32 v10, v10, v230
	global_store_dword v240, v10, s[98:99] offset:128
	v_mul_f32_e32 v14, v14, v230
	global_store_dword v240, v14, s[98:99] offset:192
	v_mul_f32_e32 v18, v18, v230
	global_store_dword v240, v18, s[98:99] offset:256
	v_mul_f32_e32 v22, v22, v230
	global_store_dword v240, v22, s[98:99] offset:320
	v_mul_f32_e32 v26, v26, v230
	global_store_dword v240, v26, s[98:99] offset:384
	v_mul_f32_e32 v30, v30, v230
	global_store_dword v240, v30, s[98:99] offset:448
	v_add_u32_e32 v240, 1536, v200
	v_mul_f32_e32 v3, v3, v231
	global_store_dword v240, v3, s[98:99] offset:0
	v_mul_f32_e32 v7, v7, v231
	global_store_dword v240, v7, s[98:99] offset:64
	v_mul_f32_e32 v11, v11, v231
	global_store_dword v240, v11, s[98:99] offset:128
	v_mul_f32_e32 v15, v15, v231
	global_store_dword v240, v15, s[98:99] offset:192
	v_mul_f32_e32 v19, v19, v231
	global_store_dword v240, v19, s[98:99] offset:256
	v_mul_f32_e32 v23, v23, v231
	global_store_dword v240, v23, s[98:99] offset:320
	v_mul_f32_e32 v27, v27, v231
	global_store_dword v240, v27, s[98:99] offset:384
	v_mul_f32_e32 v31, v31, v231
	global_store_dword v240, v31, s[98:99] offset:448
	v_add_u32_e32 v240, 8192, v200
	v_mul_f32_e32 v32, v32, v232
	global_store_dword v240, v32, s[98:99] offset:0
	v_mul_f32_e32 v36, v36, v232
	global_store_dword v240, v36, s[98:99] offset:64
	v_mul_f32_e32 v40, v40, v232
	global_store_dword v240, v40, s[98:99] offset:128
	v_mul_f32_e32 v44, v44, v232
	global_store_dword v240, v44, s[98:99] offset:192
	v_mul_f32_e32 v48, v48, v232
	global_store_dword v240, v48, s[98:99] offset:256
	v_mul_f32_e32 v52, v52, v232
	global_store_dword v240, v52, s[98:99] offset:320
	v_mul_f32_e32 v56, v56, v232
	global_store_dword v240, v56, s[98:99] offset:384
	v_mul_f32_e32 v60, v60, v232
	global_store_dword v240, v60, s[98:99] offset:448
	v_add_u32_e32 v240, 8704, v200
	v_mul_f32_e32 v33, v33, v233
	global_store_dword v240, v33, s[98:99] offset:0
	v_mul_f32_e32 v37, v37, v233
	global_store_dword v240, v37, s[98:99] offset:64
	v_mul_f32_e32 v41, v41, v233
	global_store_dword v240, v41, s[98:99] offset:128
	v_mul_f32_e32 v45, v45, v233
	global_store_dword v240, v45, s[98:99] offset:192
	v_mul_f32_e32 v49, v49, v233
	global_store_dword v240, v49, s[98:99] offset:256
	v_mul_f32_e32 v53, v53, v233
	global_store_dword v240, v53, s[98:99] offset:320
	v_mul_f32_e32 v57, v57, v233
	global_store_dword v240, v57, s[98:99] offset:384
	v_mul_f32_e32 v61, v61, v233
	global_store_dword v240, v61, s[98:99] offset:448
	v_add_u32_e32 v240, 9216, v200
	v_mul_f32_e32 v34, v34, v234
	global_store_dword v240, v34, s[98:99] offset:0
	v_mul_f32_e32 v38, v38, v234
	global_store_dword v240, v38, s[98:99] offset:64
	v_mul_f32_e32 v42, v42, v234
	global_store_dword v240, v42, s[98:99] offset:128
	v_mul_f32_e32 v46, v46, v234
	global_store_dword v240, v46, s[98:99] offset:192
	v_mul_f32_e32 v50, v50, v234
	global_store_dword v240, v50, s[98:99] offset:256
	v_mul_f32_e32 v54, v54, v234
	global_store_dword v240, v54, s[98:99] offset:320
	v_mul_f32_e32 v58, v58, v234
	global_store_dword v240, v58, s[98:99] offset:384
	v_mul_f32_e32 v62, v62, v234
	global_store_dword v240, v62, s[98:99] offset:448
	v_add_u32_e32 v240, 9728, v200
	v_mul_f32_e32 v35, v35, v235
	global_store_dword v240, v35, s[98:99] offset:0
	v_mul_f32_e32 v39, v39, v235
	global_store_dword v240, v39, s[98:99] offset:64
	v_mul_f32_e32 v43, v43, v235
	global_store_dword v240, v43, s[98:99] offset:128
	v_mul_f32_e32 v47, v47, v235
	global_store_dword v240, v47, s[98:99] offset:192
	v_mul_f32_e32 v51, v51, v235
	global_store_dword v240, v51, s[98:99] offset:256
	v_mul_f32_e32 v55, v55, v235
	global_store_dword v240, v55, s[98:99] offset:320
	v_mul_f32_e32 v59, v59, v235
	global_store_dword v240, v59, s[98:99] offset:384
	v_mul_f32_e32 v63, v63, v235
	global_store_dword v240, v63, s[98:99] offset:448
	s_waitcnt vmcnt(0)
	s_cmp_eq_u32 s6, 0
	s_cbranch_scc1 .LBB0_456
	s_lshl_b32 s85, s85, 7
	s_branch .La16_combine
.La16_combine:
	s_andn2_b64 vcc, exec, s[50:51]
	s_waitcnt vmcnt(63) expcnt(7) lgkmcnt(15)
	s_barrier
	s_cbranch_vccnz .LBB0_455
	global_load_dwordx2 v[0:1], v[134:135], off
	v_and_b32_e32 v2, 64, v211
	v_add_u32_e32 v4, 64, v2
	v_xor_b32_e32 v5, 1, v211
	v_cmp_lt_i32_e32 vcc, v5, v4
	s_lshl_b32 s48, s85, 1
	v_lshl_add_u64 v[2:3], v[136:137], 0, s[48:49]
	v_cndmask_b32_e32 v5, v211, v5, vcc
	v_lshlrev_b32_e32 v6, 2, v5
	v_xor_b32_e32 v5, 2, v211
	v_cmp_lt_i32_e32 vcc, v5, v4
	s_mov_b32 s10, s33
	s_nop 0
	v_cndmask_b32_e32 v5, v211, v5, vcc
	v_lshlrev_b32_e32 v7, 2, v5
	v_xor_b32_e32 v5, 4, v211
	v_cmp_lt_i32_e32 vcc, v5, v4
	s_nop 1
	v_cndmask_b32_e32 v5, v211, v5, vcc
	v_lshlrev_b32_e32 v8, 2, v5
	v_xor_b32_e32 v5, 8, v211
	v_cmp_lt_i32_e32 vcc, v5, v4
	s_nop 1
	v_cndmask_b32_e32 v5, v211, v5, vcc
	v_lshlrev_b32_e32 v9, 2, v5
	v_xor_b32_e32 v5, 16, v211
	v_cmp_lt_i32_e32 vcc, v5, v4
	s_nop 1
	v_cndmask_b32_e32 v5, v211, v5, vcc
	v_lshlrev_b32_e32 v10, 2, v5
	v_xor_b32_e32 v5, 32, v211
	v_cmp_lt_i32_e32 vcc, v5, v4
	s_nop 1
	v_cndmask_b32_e32 v4, v211, v5, vcc
	v_lshlrev_b32_e32 v11, 2, v4
	v_mov_b64_e32 v[4:5], v[140:141]

	.amdhsa_kernel _Z8fwd_mega4Args
		.amdhsa_group_segment_fixed_size 0
		.amdhsa_private_segment_fixed_size 0
		.amdhsa_kernarg_size 432
		.amdhsa_user_sgpr_count 2
		.amdhsa_user_sgpr_dispatch_ptr 0
		.amdhsa_user_sgpr_queue_ptr 0
		.amdhsa_user_sgpr_kernarg_segment_ptr 1
		.amdhsa_user_sgpr_dispatch_id 0
		.amdhsa_user_sgpr_kernarg_preload_length 0
		.amdhsa_user_sgpr_kernarg_preload_offset 0
		.amdhsa_user_sgpr_private_segment_size 0
		.amdhsa_uses_dynamic_stack 0
		.amdhsa_enable_private_segment 0
		.amdhsa_system_sgpr_workgroup_id_x 1
		.amdhsa_system_sgpr_workgroup_id_y 0
		.amdhsa_system_sgpr_workgroup_id_z 0
		.amdhsa_system_sgpr_workgroup_info 0
		.amdhsa_system_vgpr_workitem_id 2
		.amdhsa_next_free_vgpr 256
		.amdhsa_next_free_sgpr 100
		.amdhsa_accum_offset 256
		.amdhsa_reserve_vcc 1
		.amdhsa_float_round_mode_32 0
		.amdhsa_float_round_mode_16_64 0
		.amdhsa_float_denorm_mode_32 3
		.amdhsa_float_denorm_mode_16_64 3
		.amdhsa_dx10_clamp 1
		.amdhsa_ieee_mode 1
		.amdhsa_fp16_overflow 0
		.amdhsa_tg_split 0
		.amdhsa_exception_fp_ieee_invalid_op 0
		.amdhsa_exception_fp_denorm_src 0
		.amdhsa_exception_fp_ieee_div_zero 0
		.amdhsa_exception_fp_ieee_overflow 0
		.amdhsa_exception_fp_ieee_underflow 0
		.amdhsa_exception_fp_ieee_inexact 0
		.amdhsa_exception_int_div_zero 0
	.end_amdhsa_kernel

amdhsa.kernels:
  - .agpr_count:     0
    .args:
      - .offset:         0
        .size:           176
        .value_kind:     by_value
      - .offset:         176
        .size:           4
        .value_kind:     hidden_block_count_x
      - .offset:         180
        .size:           4
        .value_kind:     hidden_block_count_y
      - .offset:         184
        .size:           4
        .value_kind:     hidden_block_count_z
      - .offset:         188
        .size:           2
        .value_kind:     hidden_group_size_x
      - .offset:         190
        .size:           2
        .value_kind:     hidden_group_size_y
      - .offset:         192
        .size:           2
        .value_kind:     hidden_group_size_z
      - .offset:         194
        .size:           2
        .value_kind:     hidden_remainder_x
      - .offset:         196
        .size:           2
        .value_kind:     hidden_remainder_y
      - .offset:         198
        .size:           2
        .value_kind:     hidden_remainder_z
      - .offset:         216
        .size:           8
        .value_kind:     hidden_global_offset_x
      - .offset:         224
        .size:           8
        .value_kind:     hidden_global_offset_y
      - .offset:         232
        .size:           8
        .value_kind:     hidden_global_offset_z
      - .offset:         240
        .size:           2
        .value_kind:     hidden_grid_dims
      - .offset:         264
        .size:           8
        .value_kind:     hidden_multigrid_sync_arg
      - .offset:         296
        .size:           4
        .value_kind:     hidden_dynamic_lds_size
    .group_segment_fixed_size: 0
    .kernarg_segment_align: 8
    .kernarg_segment_size: 432
    .language:       OpenCL C
    .language_version:
      - 2
      - 0
    .max_flat_workgroup_size: 512
    .name:           _Z8fwd_mega4Args
    .private_segment_fixed_size: 0
    .sgpr_count:     106
    .sgpr_spill_count: 12
    .symbol:         _Z8fwd_mega4Args.kd
    .uniform_work_group_size: 1
    .uses_dynamic_stack: false
    .vgpr_count:     256
    .vgpr_spill_count: 0
    .wavefront_size: 64
